# v39 + Proj epilogue rewritten: one activation-mode dispatch per tile instead of uniform branches in every row group, packed f32 math, rstd for all 8 row groups up front
# baseline (speedup 1.0000x reference)
; __device__ __forceinline__ unsigned cvt_pk_bf16(float lo, float hi) { unsigned r; asm volatile("v_cvt_pk_bf16_f32 %0, %1, %2" : "=v"(r) : "v"(lo), "v"(hi)); return r; }
; __device__ __forceinline__ float silu_f(float g) { return g * __builtin_amdgcn_rcpf(1.0f + __expf(-g)); }
; __device__ __forceinline__ float sigm_f(float g) { return __builtin_amdgcn_rcpf(1.0f + __expf(-g)); }
;     __device__ __forceinline__ void operator()(const f32x4 (&acc)[2][2][4][2], const Unit& u, int wr, int wc, int fr, int fq) const {
;         const int r00 = u.pm * BM;
;         const int b = r00 < 32768 ? (r00 >> 11) : 16 + ((r00 - 32768) >> 12);
;         const int row0 = r00 + wr * 64 + fr; const int col0 = u.pn * BM + wc * 32 + 8 * fq;
;         const int mode = (u.pn < 2 || u.pn == 8 || u.pn == 9) ? 1 : ((u.pn >= 2 && u.pn < 6) ? 2 : 0);
;         const float* sp = shw + (size_t)b * 5632 + col0;
;         f32x4 sv[2][2];
; #pragma unroll
;         for (int bj = 0; bj < 2; ++bj) { sv[bj][0] = *(const f32x4*)(sp + bj * HALF); sv[bj][1] = *(const f32x4*)(sp + bj * HALF + 4); }
; #pragma unroll
;         for (int ai = 0; ai < 2; ++ai)
; #pragma unroll
;             for (int m = 0; m < 4; ++m) { const int row = row0 + ai * HALF + m * 16;
;                 const float rs = __builtin_amdgcn_rsqf(ssq[row] * (1.0f / 1024.0f) + 1e-6f);
;                 bf16_t* rowp = O + (size_t)row * 4224 + col0;
; #pragma unroll
;                 for (int bj = 0; bj < 2; ++bj) { f32x4 v0 = acc[ai][bj][m][0] * rs + sv[bj][0], v1 = acc[ai][bj][m][1] * rs + sv[bj][1];
;                     if (mode == 1) {
; #pragma unroll
;                         for (int e = 0; e < 4; ++e) { v0[e] = silu_f(v0[e]); v1[e] = silu_f(v1[e]); }
;                     } else if (mode == 2) {
; #pragma unroll
;                         for (int e = 0; e < 4; ++e) { v0[e] = sigm_f(v0[e]); v1[e] = sigm_f(v1[e]); }
;                     }
;                     u32x4 w; w.x = cvt_pk_bf16(v0[0], v0[1]); w.y = cvt_pk_bf16(v0[2], v0[3]); w.z = cvt_pk_bf16(v1[0], v1[1]); w.w = cvt_pk_bf16(v1[2], v1[3]);
;                     *(u32x4*)(rowp + bj * HALF) = w; } }
.LBB0_200:
	s_lshl_b32 s9, s0, 8
	s_add_i32 s17, s9, 0xffff8000
	v_add_u32_e32 v156, s9, v175
	s_lshr_b32 s17, s17, 12
	v_ashrrev_i32_e32 v157, 31, v156
	s_ashr_i32 s16, s0, 3
	s_add_i32 s17, s17, 16
	v_lshl_add_u64 v[158:159], v[156:157], 2, s[44:45]
	s_cmpk_lt_i32 s0, 0x80
	global_load_dword v157, v[158:159], off
	global_load_dword v192, v[158:159], off offset:64
	global_load_dword v193, v[158:159], off offset:128
	global_load_dword v194, v[158:159], off offset:192
	global_load_dword v195, v[158:159], off offset:512
	global_load_dword v196, v[158:159], off offset:576
	global_load_dword v197, v[158:159], off offset:640
	global_load_dword v198, v[158:159], off offset:704
	s_cselect_b32 s0, s16, s17
	s_and_b32 s16, s1, -2
	s_cmp_eq_u32 s16, 8
	s_cselect_b64 s[16:17], -1, 0
	s_cmp_lt_i32 s1, 6
	s_mul_hi_i32 s21, s0, 0x5800
	s_mulk_i32 s0, 0x5800
	v_lshl_or_b32 v154, s1, 8, v179
	s_cselect_b32 s39, 2, 0
	s_add_u32 s20, s22, s0
	s_addc_u32 s21, s65, s21
	v_ashrrev_i32_e32 v155, 31, v154
	v_lshl_add_u64 v[28:29], v[154:155], 2, s[20:21]
	global_load_dwordx4 v[44:47], v[28:29], off
	global_load_dwordx4 v[40:43], v[28:29], off offset:16
	global_load_dwordx4 v[24:27], v[28:29], off offset:528
	s_nop 0
	global_load_dwordx4 v[28:31], v[28:29], off offset:512
	s_cmp_lt_i32 s1, 2
	s_cselect_b64 s[0:1], -1, 0
	s_or_b64 s[0:1], s[0:1], s[16:17]
	s_and_b64 s[0:1], s[0:1], exec
	s_cselect_b32 s49, 1, s39
	s_cmp_gt_i32 s49, 1
	s_mov_b64 s[40:41], -1
	s_waitcnt vmcnt(0)
	v_mov_b32_e32 v216, 0xbfb8aa3b
	v_fmamk_f32 v200, v157, 0x3a800000, v224
	v_fmamk_f32 v202, v192, 0x3a800000, v224
	v_fmamk_f32 v204, v193, 0x3a800000, v224
	v_fmamk_f32 v206, v194, 0x3a800000, v224
	v_fmamk_f32 v208, v195, 0x3a800000, v224
	v_fmamk_f32 v210, v196, 0x3a800000, v224
	v_fmamk_f32 v212, v197, 0x3a800000, v224
	v_fmamk_f32 v214, v198, 0x3a800000, v224
	v_rsq_f32_e32 v200, v200
	v_rsq_f32_e32 v202, v202
	v_rsq_f32_e32 v204, v204
	v_rsq_f32_e32 v206, v206
	v_rsq_f32_e32 v208, v208
	v_rsq_f32_e32 v210, v210
	v_rsq_f32_e32 v212, v212
	v_rsq_f32_e32 v214, v214
	s_cmp_eq_u32 s49, 1
	s_cbranch_scc1 .Lpj_silu
	s_cmp_eq_u32 s49, 2
	s_cbranch_scc1 .Lpj_sigm
	v_mov_b32_e32 v190, v156
	v_mov_b64_e32 v[192:193], s[12:13]
	v_mad_i64_i32 v[190:191], s[0:1], v190, s66, v[192:193]
	v_lshl_add_u64 v[190:191], v[154:155], 1, v[190:191]
	v_pk_fma_f32 v[140:141], v[140:141], v[200:201], v[44:45] op_sel_hi:[1,0,1]
	v_pk_fma_f32 v[142:143], v[142:143], v[200:201], v[46:47] op_sel_hi:[1,0,1]
	v_pk_fma_f32 v[136:137], v[136:137], v[200:201], v[40:41] op_sel_hi:[1,0,1]
	v_pk_fma_f32 v[138:139], v[138:139], v[200:201], v[42:43] op_sel_hi:[1,0,1]
	v_cvt_pk_bf16_f32 v238, v140, v141
	v_cvt_pk_bf16_f32 v239, v142, v143
	v_cvt_pk_bf16_f32 v240, v136, v137
	v_cvt_pk_bf16_f32 v241, v138, v139
	global_store_dwordx4 v[190:191], v[238:241], off
	v_pk_fma_f32 v[132:133], v[132:133], v[200:201], v[28:29] op_sel_hi:[1,0,1]
	v_pk_fma_f32 v[134:135], v[134:135], v[200:201], v[30:31] op_sel_hi:[1,0,1]
	v_pk_fma_f32 v[128:129], v[128:129], v[200:201], v[24:25] op_sel_hi:[1,0,1]
	v_pk_fma_f32 v[130:131], v[130:131], v[200:201], v[26:27] op_sel_hi:[1,0,1]
	v_cvt_pk_bf16_f32 v218, v132, v133
	v_cvt_pk_bf16_f32 v219, v134, v135
	v_cvt_pk_bf16_f32 v220, v128, v129
	v_cvt_pk_bf16_f32 v221, v130, v131
	global_store_dwordx4 v[190:191], v[218:221], off offset:256
	v_or_b32_e32 v190, 16, v156
	v_mov_b64_e32 v[192:193], s[12:13]
	v_mad_i64_i32 v[190:191], s[0:1], v190, s66, v[192:193]
	v_lshl_add_u64 v[190:191], v[154:155], 1, v[190:191]
	v_pk_fma_f32 v[124:125], v[124:125], v[202:203], v[44:45] op_sel_hi:[1,0,1]
	v_pk_fma_f32 v[126:127], v[126:127], v[202:203], v[46:47] op_sel_hi:[1,0,1]
	v_pk_fma_f32 v[120:121], v[120:121], v[202:203], v[40:41] op_sel_hi:[1,0,1]
	v_pk_fma_f32 v[122:123], v[122:123], v[202:203], v[42:43] op_sel_hi:[1,0,1]
	v_cvt_pk_bf16_f32 v238, v124, v125
	v_cvt_pk_bf16_f32 v239, v126, v127
	v_cvt_pk_bf16_f32 v240, v120, v121
	v_cvt_pk_bf16_f32 v241, v122, v123
	global_store_dwordx4 v[190:191], v[238:241], off
	v_pk_fma_f32 v[116:117], v[116:117], v[202:203], v[28:29] op_sel_hi:[1,0,1]
	v_pk_fma_f32 v[118:119], v[118:119], v[202:203], v[30:31] op_sel_hi:[1,0,1]
	v_pk_fma_f32 v[112:113], v[112:113], v[202:203], v[24:25] op_sel_hi:[1,0,1]
	v_pk_fma_f32 v[114:115], v[114:115], v[202:203], v[26:27] op_sel_hi:[1,0,1]
	v_cvt_pk_bf16_f32 v218, v116, v117
	v_cvt_pk_bf16_f32 v219, v118, v119
	v_cvt_pk_bf16_f32 v220, v112, v113
	v_cvt_pk_bf16_f32 v221, v114, v115
	global_store_dwordx4 v[190:191], v[218:221], off offset:256
	v_or_b32_e32 v190, 32, v156
	v_mov_b64_e32 v[192:193], s[12:13]
	v_mad_i64_i32 v[190:191], s[0:1], v190, s66, v[192:193]
	v_lshl_add_u64 v[190:191], v[154:155], 1, v[190:191]
	v_pk_fma_f32 v[108:109], v[108:109], v[204:205], v[44:45] op_sel_hi:[1,0,1]
	v_pk_fma_f32 v[110:111], v[110:111], v[204:205], v[46:47] op_sel_hi:[1,0,1]
	v_pk_fma_f32 v[104:105], v[104:105], v[204:205], v[40:41] op_sel_hi:[1,0,1]
	v_pk_fma_f32 v[106:107], v[106:107], v[204:205], v[42:43] op_sel_hi:[1,0,1]
	v_cvt_pk_bf16_f32 v238, v108, v109
	v_cvt_pk_bf16_f32 v239, v110, v111
	v_cvt_pk_bf16_f32 v240, v104, v105
	v_cvt_pk_bf16_f32 v241, v106, v107
	global_store_dwordx4 v[190:191], v[238:241], off
	v_pk_fma_f32 v[100:101], v[100:101], v[204:205], v[28:29] op_sel_hi:[1,0,1]
	v_pk_fma_f32 v[102:103], v[102:103], v[204:205], v[30:31] op_sel_hi:[1,0,1]
	v_pk_fma_f32 v[96:97], v[96:97], v[204:205], v[24:25] op_sel_hi:[1,0,1]
	v_pk_fma_f32 v[98:99], v[98:99], v[204:205], v[26:27] op_sel_hi:[1,0,1]
	v_cvt_pk_bf16_f32 v218, v100, v101
	v_cvt_pk_bf16_f32 v219, v102, v103
	v_cvt_pk_bf16_f32 v220, v96, v97
	v_cvt_pk_bf16_f32 v221, v98, v99
; __device__ __forceinline__ unsigned cvt_pk_bf16(float lo, float hi) { unsigned r; asm volatile("v_cvt_pk_bf16_f32 %0, %1, %2" : "=v"(r) : "v"(lo), "v"(hi)); return r; }
; __device__ __forceinline__ float silu_f(float g) { return g * __builtin_amdgcn_rcpf(1.0f + __expf(-g)); }
; __device__ __forceinline__ float sigm_f(float g) { return __builtin_amdgcn_rcpf(1.0f + __expf(-g)); }
;     __device__ __forceinline__ void operator()(const f32x4 (&acc)[2][2][4][2], const Unit& u, int wr, int wc, int fr, int fq) const {
;     ...
;             for (int m = 0; m < 4; ++m) { const int row = row0 + ai * HALF + m * 16;
;                 const float rs = __builtin_amdgcn_rsqf(ssq[row] * (1.0f / 1024.0f) + 1e-6f);
;                 bf16_t* rowp = O + (size_t)row * 4224 + col0;
; #pragma unroll
;                 for (int bj = 0; bj < 2; ++bj) { f32x4 v0 = acc[ai][bj][m][0] * rs + sv[bj][0], v1 = acc[ai][bj][m][1] * rs + sv[bj][1];
;                     if (mode == 1) {
; #pragma unroll
;                         for (int e = 0; e < 4; ++e) { v0[e] = silu_f(v0[e]); v1[e] = silu_f(v1[e]); }
;                     } else if (mode == 2) {
; #pragma unroll
;                         for (int e = 0; e < 4; ++e) { v0[e] = sigm_f(v0[e]); v1[e] = sigm_f(v1[e]); }
;                     }
;                     u32x4 w; w.x = cvt_pk_bf16(v0[0], v0[1]); w.y = cvt_pk_bf16(v0[2], v0[3]); w.z = cvt_pk_bf16(v1[0], v1[1]); w.w = cvt_pk_bf16(v1[2], v1[3]);
;                     *(u32x4*)(rowp + bj * HALF) = w; } }
	global_store_dwordx4 v[190:191], v[218:221], off offset:256
	v_or_b32_e32 v190, 48, v156
	v_mov_b64_e32 v[192:193], s[12:13]
	v_mad_i64_i32 v[190:191], s[0:1], v190, s66, v[192:193]
	v_lshl_add_u64 v[190:191], v[154:155], 1, v[190:191]
	v_pk_fma_f32 v[92:93], v[92:93], v[206:207], v[44:45] op_sel_hi:[1,0,1]
	v_pk_fma_f32 v[94:95], v[94:95], v[206:207], v[46:47] op_sel_hi:[1,0,1]
	v_pk_fma_f32 v[88:89], v[88:89], v[206:207], v[40:41] op_sel_hi:[1,0,1]
	v_pk_fma_f32 v[90:91], v[90:91], v[206:207], v[42:43] op_sel_hi:[1,0,1]
	v_cvt_pk_bf16_f32 v238, v92, v93
	v_cvt_pk_bf16_f32 v239, v94, v95
	v_cvt_pk_bf16_f32 v240, v88, v89
	v_cvt_pk_bf16_f32 v241, v90, v91
	global_store_dwordx4 v[190:191], v[238:241], off
	v_pk_fma_f32 v[84:85], v[84:85], v[206:207], v[28:29] op_sel_hi:[1,0,1]
	v_pk_fma_f32 v[86:87], v[86:87], v[206:207], v[30:31] op_sel_hi:[1,0,1]
	v_pk_fma_f32 v[80:81], v[80:81], v[206:207], v[24:25] op_sel_hi:[1,0,1]
	v_pk_fma_f32 v[82:83], v[82:83], v[206:207], v[26:27] op_sel_hi:[1,0,1]
	v_cvt_pk_bf16_f32 v218, v84, v85
	v_cvt_pk_bf16_f32 v219, v86, v87
	v_cvt_pk_bf16_f32 v220, v80, v81
	v_cvt_pk_bf16_f32 v221, v82, v83
	global_store_dwordx4 v[190:191], v[218:221], off offset:256
	v_add_u32_e32 v190, 0x80, v156
	v_mov_b64_e32 v[192:193], s[12:13]
	v_mad_i64_i32 v[190:191], s[0:1], v190, s66, v[192:193]
	v_lshl_add_u64 v[190:191], v[154:155], 1, v[190:191]
	v_pk_fma_f32 v[76:77], v[76:77], v[208:209], v[44:45] op_sel_hi:[1,0,1]
	v_pk_fma_f32 v[78:79], v[78:79], v[208:209], v[46:47] op_sel_hi:[1,0,1]
	v_pk_fma_f32 v[72:73], v[72:73], v[208:209], v[40:41] op_sel_hi:[1,0,1]
	v_pk_fma_f32 v[74:75], v[74:75], v[208:209], v[42:43] op_sel_hi:[1,0,1]
	v_cvt_pk_bf16_f32 v238, v76, v77
	v_cvt_pk_bf16_f32 v239, v78, v79
	v_cvt_pk_bf16_f32 v240, v72, v73
	v_cvt_pk_bf16_f32 v241, v74, v75
	global_store_dwordx4 v[190:191], v[238:241], off
	v_pk_fma_f32 v[68:69], v[68:69], v[208:209], v[28:29] op_sel_hi:[1,0,1]
	v_pk_fma_f32 v[70:71], v[70:71], v[208:209], v[30:31] op_sel_hi:[1,0,1]
	v_pk_fma_f32 v[64:65], v[64:65], v[208:209], v[24:25] op_sel_hi:[1,0,1]
	v_pk_fma_f32 v[66:67], v[66:67], v[208:209], v[26:27] op_sel_hi:[1,0,1]
	v_cvt_pk_bf16_f32 v218, v68, v69
	v_cvt_pk_bf16_f32 v219, v70, v71
	v_cvt_pk_bf16_f32 v220, v64, v65
	v_cvt_pk_bf16_f32 v221, v66, v67
	global_store_dwordx4 v[190:191], v[218:221], off offset:256
	v_add_u32_e32 v190, 0x90, v156
	v_mov_b64_e32 v[192:193], s[12:13]
	v_mad_i64_i32 v[190:191], s[0:1], v190, s66, v[192:193]
	v_lshl_add_u64 v[190:191], v[154:155], 1, v[190:191]
	v_pk_fma_f32 v[60:61], v[60:61], v[210:211], v[44:45] op_sel_hi:[1,0,1]
	v_pk_fma_f32 v[62:63], v[62:63], v[210:211], v[46:47] op_sel_hi:[1,0,1]
	v_pk_fma_f32 v[56:57], v[56:57], v[210:211], v[40:41] op_sel_hi:[1,0,1]
	v_pk_fma_f32 v[58:59], v[58:59], v[210:211], v[42:43] op_sel_hi:[1,0,1]
	v_cvt_pk_bf16_f32 v238, v60, v61
	v_cvt_pk_bf16_f32 v239, v62, v63
	v_cvt_pk_bf16_f32 v240, v56, v57
	v_cvt_pk_bf16_f32 v241, v58, v59
	global_store_dwordx4 v[190:191], v[238:241], off
	v_pk_fma_f32 v[52:53], v[52:53], v[210:211], v[28:29] op_sel_hi:[1,0,1]
	v_pk_fma_f32 v[54:55], v[54:55], v[210:211], v[30:31] op_sel_hi:[1,0,1]
	v_pk_fma_f32 v[48:49], v[48:49], v[210:211], v[24:25] op_sel_hi:[1,0,1]
	v_pk_fma_f32 v[50:51], v[50:51], v[210:211], v[26:27] op_sel_hi:[1,0,1]
	v_cvt_pk_bf16_f32 v218, v52, v53
	v_cvt_pk_bf16_f32 v219, v54, v55
	v_cvt_pk_bf16_f32 v220, v48, v49
	v_cvt_pk_bf16_f32 v221, v50, v51
	global_store_dwordx4 v[190:191], v[218:221], off offset:256
	v_add_u32_e32 v190, 0xa0, v156
	v_mov_b64_e32 v[192:193], s[12:13]
	v_mad_i64_i32 v[190:191], s[0:1], v190, s66, v[192:193]
	v_lshl_add_u64 v[190:191], v[154:155], 1, v[190:191]
	v_pk_fma_f32 v[36:37], v[36:37], v[212:213], v[44:45] op_sel_hi:[1,0,1]
	v_pk_fma_f32 v[38:39], v[38:39], v[212:213], v[46:47] op_sel_hi:[1,0,1]
	v_pk_fma_f32 v[32:33], v[32:33], v[212:213], v[40:41] op_sel_hi:[1,0,1]
	v_pk_fma_f32 v[34:35], v[34:35], v[212:213], v[42:43] op_sel_hi:[1,0,1]
	v_cvt_pk_bf16_f32 v238, v36, v37
	v_cvt_pk_bf16_f32 v239, v38, v39
	v_cvt_pk_bf16_f32 v240, v32, v33
	v_cvt_pk_bf16_f32 v241, v34, v35
	global_store_dwordx4 v[190:191], v[238:241], off
	v_pk_fma_f32 v[20:21], v[20:21], v[212:213], v[28:29] op_sel_hi:[1,0,1]
	v_pk_fma_f32 v[22:23], v[22:23], v[212:213], v[30:31] op_sel_hi:[1,0,1]
	v_pk_fma_f32 v[16:17], v[16:17], v[212:213], v[24:25] op_sel_hi:[1,0,1]
	v_pk_fma_f32 v[18:19], v[18:19], v[212:213], v[26:27] op_sel_hi:[1,0,1]
	v_cvt_pk_bf16_f32 v218, v20, v21
	v_cvt_pk_bf16_f32 v219, v22, v23
	v_cvt_pk_bf16_f32 v220, v16, v17
	v_cvt_pk_bf16_f32 v221, v18, v19
	global_store_dwordx4 v[190:191], v[218:221], off offset:256
	v_add_u32_e32 v190, 0xb0, v156
	v_mov_b64_e32 v[192:193], s[12:13]
	v_mad_i64_i32 v[190:191], s[0:1], v190, s66, v[192:193]
	v_lshl_add_u64 v[190:191], v[154:155], 1, v[190:191]
	v_pk_fma_f32 v[12:13], v[12:13], v[214:215], v[44:45] op_sel_hi:[1,0,1]
	v_pk_fma_f32 v[14:15], v[14:15], v[214:215], v[46:47] op_sel_hi:[1,0,1]
	v_pk_fma_f32 v[8:9], v[8:9], v[214:215], v[40:41] op_sel_hi:[1,0,1]
	v_pk_fma_f32 v[10:11], v[10:11], v[214:215], v[42:43] op_sel_hi:[1,0,1]
	v_cvt_pk_bf16_f32 v238, v12, v13
	v_cvt_pk_bf16_f32 v239, v14, v15
	v_cvt_pk_bf16_f32 v240, v8, v9
	v_cvt_pk_bf16_f32 v241, v10, v11
	global_store_dwordx4 v[190:191], v[238:241], off
	v_pk_fma_f32 v[4:5], v[4:5], v[214:215], v[28:29] op_sel_hi:[1,0,1]
	v_pk_fma_f32 v[6:7], v[6:7], v[214:215], v[30:31] op_sel_hi:[1,0,1]
	v_pk_fma_f32 v[0:1], v[0:1], v[214:215], v[24:25] op_sel_hi:[1,0,1]
	v_pk_fma_f32 v[2:3], v[2:3], v[214:215], v[26:27] op_sel_hi:[1,0,1]
	v_cvt_pk_bf16_f32 v218, v4, v5
	v_cvt_pk_bf16_f32 v219, v6, v7
	v_cvt_pk_bf16_f32 v220, v0, v1
	v_cvt_pk_bf16_f32 v221, v2, v3
	global_store_dwordx4 v[190:191], v[218:221], off offset:256
	s_branch .Lpj_done
; __device__ __forceinline__ unsigned cvt_pk_bf16(float lo, float hi) { unsigned r; asm volatile("v_cvt_pk_bf16_f32 %0, %1, %2" : "=v"(r) : "v"(lo), "v"(hi)); return r; }
; __device__ __forceinline__ float silu_f(float g) { return g * __builtin_amdgcn_rcpf(1.0f + __expf(-g)); }
; __device__ __forceinline__ float sigm_f(float g) { return __builtin_amdgcn_rcpf(1.0f + __expf(-g)); }
;     __device__ __forceinline__ void operator()(const f32x4 (&acc)[2][2][4][2], const Unit& u, int wr, int wc, int fr, int fq) const {
;     ...
;             for (int m = 0; m < 4; ++m) { const int row = row0 + ai * HALF + m * 16;
;                 const float rs = __builtin_amdgcn_rsqf(ssq[row] * (1.0f / 1024.0f) + 1e-6f);
;                 bf16_t* rowp = O + (size_t)row * 4224 + col0;
; #pragma unroll
;                 for (int bj = 0; bj < 2; ++bj) { f32x4 v0 = acc[ai][bj][m][0] * rs + sv[bj][0], v1 = acc[ai][bj][m][1] * rs + sv[bj][1];
;                     if (mode == 1) {
; #pragma unroll
;                         for (int e = 0; e < 4; ++e) { v0[e] = silu_f(v0[e]); v1[e] = silu_f(v1[e]); }
;                     } else if (mode == 2) {
; #pragma unroll
;                         for (int e = 0; e < 4; ++e) { v0[e] = sigm_f(v0[e]); v1[e] = sigm_f(v1[e]); }
;                     }
;                     u32x4 w; w.x = cvt_pk_bf16(v0[0], v0[1]); w.y = cvt_pk_bf16(v0[2], v0[3]); w.z = cvt_pk_bf16(v1[0], v1[1]); w.w = cvt_pk_bf16(v1[2], v1[3]);
;                     *(u32x4*)(rowp + bj * HALF) = w; } }
.Lpj_silu:
	v_mov_b32_e32 v190, v156
	v_mov_b64_e32 v[192:193], s[12:13]
	v_mad_i64_i32 v[190:191], s[0:1], v190, s66, v[192:193]
	v_lshl_add_u64 v[190:191], v[154:155], 1, v[190:191]
	v_pk_fma_f32 v[140:141], v[140:141], v[200:201], v[44:45] op_sel_hi:[1,0,1]
	v_pk_fma_f32 v[142:143], v[142:143], v[200:201], v[46:47] op_sel_hi:[1,0,1]
	v_pk_fma_f32 v[136:137], v[136:137], v[200:201], v[40:41] op_sel_hi:[1,0,1]
	v_pk_fma_f32 v[138:139], v[138:139], v[200:201], v[42:43] op_sel_hi:[1,0,1]
	v_pk_mul_f32 v[192:193], v[140:141], v[216:217] op_sel_hi:[1,0]
	v_pk_mul_f32 v[194:195], v[142:143], v[216:217] op_sel_hi:[1,0]
	v_pk_mul_f32 v[196:197], v[136:137], v[216:217] op_sel_hi:[1,0]
	v_pk_mul_f32 v[198:199], v[138:139], v[216:217] op_sel_hi:[1,0]
	v_exp_f32_e32 v192, v192
	v_exp_f32_e32 v193, v193
	v_exp_f32_e32 v194, v194
	v_exp_f32_e32 v195, v195
	v_exp_f32_e32 v196, v196
	v_exp_f32_e32 v197, v197
	v_exp_f32_e32 v198, v198
	v_exp_f32_e32 v199, v199
	v_pk_add_f32 v[192:193], v[192:193], 1.0 op_sel_hi:[1,0]
	v_pk_add_f32 v[194:195], v[194:195], 1.0 op_sel_hi:[1,0]
	v_pk_add_f32 v[196:197], v[196:197], 1.0 op_sel_hi:[1,0]
	v_pk_add_f32 v[198:199], v[198:199], 1.0 op_sel_hi:[1,0]
	v_rcp_f32_e32 v192, v192
	v_rcp_f32_e32 v193, v193
	v_rcp_f32_e32 v194, v194
	v_rcp_f32_e32 v195, v195
	v_rcp_f32_e32 v196, v196
	v_rcp_f32_e32 v197, v197
	v_rcp_f32_e32 v198, v198
	v_rcp_f32_e32 v199, v199
	v_pk_mul_f32 v[140:141], v[140:141], v[192:193]
	v_pk_mul_f32 v[142:143], v[142:143], v[194:195]
	v_pk_mul_f32 v[136:137], v[136:137], v[196:197]
	v_pk_mul_f32 v[138:139], v[138:139], v[198:199]
	v_cvt_pk_bf16_f32 v238, v140, v141
	v_cvt_pk_bf16_f32 v239, v142, v143
	v_cvt_pk_bf16_f32 v240, v136, v137
	v_cvt_pk_bf16_f32 v241, v138, v139
	global_store_dwordx4 v[190:191], v[238:241], off
	v_pk_fma_f32 v[132:133], v[132:133], v[200:201], v[28:29] op_sel_hi:[1,0,1]
	v_pk_fma_f32 v[134:135], v[134:135], v[200:201], v[30:31] op_sel_hi:[1,0,1]
	v_pk_fma_f32 v[128:129], v[128:129], v[200:201], v[24:25] op_sel_hi:[1,0,1]
	v_pk_fma_f32 v[130:131], v[130:131], v[200:201], v[26:27] op_sel_hi:[1,0,1]
	v_pk_mul_f32 v[192:193], v[132:133], v[216:217] op_sel_hi:[1,0]
	v_pk_mul_f32 v[194:195], v[134:135], v[216:217] op_sel_hi:[1,0]
	v_pk_mul_f32 v[196:197], v[128:129], v[216:217] op_sel_hi:[1,0]
	v_pk_mul_f32 v[198:199], v[130:131], v[216:217] op_sel_hi:[1,0]
	v_exp_f32_e32 v192, v192
	v_exp_f32_e32 v193, v193
	v_exp_f32_e32 v194, v194
	v_exp_f32_e32 v195, v195
	v_exp_f32_e32 v196, v196
	v_exp_f32_e32 v197, v197
	v_exp_f32_e32 v198, v198
	v_exp_f32_e32 v199, v199
	v_pk_add_f32 v[192:193], v[192:193], 1.0 op_sel_hi:[1,0]
	v_pk_add_f32 v[194:195], v[194:195], 1.0 op_sel_hi:[1,0]
	v_pk_add_f32 v[196:197], v[196:197], 1.0 op_sel_hi:[1,0]
	v_pk_add_f32 v[198:199], v[198:199], 1.0 op_sel_hi:[1,0]
	v_rcp_f32_e32 v192, v192
	v_rcp_f32_e32 v193, v193
	v_rcp_f32_e32 v194, v194
	v_rcp_f32_e32 v195, v195
	v_rcp_f32_e32 v196, v196
	v_rcp_f32_e32 v197, v197
	v_rcp_f32_e32 v198, v198
	v_rcp_f32_e32 v199, v199
	v_pk_mul_f32 v[132:133], v[132:133], v[192:193]
	v_pk_mul_f32 v[134:135], v[134:135], v[194:195]
	v_pk_mul_f32 v[128:129], v[128:129], v[196:197]
	v_pk_mul_f32 v[130:131], v[130:131], v[198:199]
	v_cvt_pk_bf16_f32 v218, v132, v133
	v_cvt_pk_bf16_f32 v219, v134, v135
	v_cvt_pk_bf16_f32 v220, v128, v129
	v_cvt_pk_bf16_f32 v221, v130, v131
	global_store_dwordx4 v[190:191], v[218:221], off offset:256
	v_or_b32_e32 v190, 16, v156
	v_mov_b64_e32 v[192:193], s[12:13]
	v_mad_i64_i32 v[190:191], s[0:1], v190, s66, v[192:193]
	v_lshl_add_u64 v[190:191], v[154:155], 1, v[190:191]
	v_pk_fma_f32 v[124:125], v[124:125], v[202:203], v[44:45] op_sel_hi:[1,0,1]
	v_pk_fma_f32 v[126:127], v[126:127], v[202:203], v[46:47] op_sel_hi:[1,0,1]
	v_pk_fma_f32 v[120:121], v[120:121], v[202:203], v[40:41] op_sel_hi:[1,0,1]
	v_pk_fma_f32 v[122:123], v[122:123], v[202:203], v[42:43] op_sel_hi:[1,0,1]
	v_pk_mul_f32 v[192:193], v[124:125], v[216:217] op_sel_hi:[1,0]
	v_pk_mul_f32 v[194:195], v[126:127], v[216:217] op_sel_hi:[1,0]
	v_pk_mul_f32 v[196:197], v[120:121], v[216:217] op_sel_hi:[1,0]
	v_pk_mul_f32 v[198:199], v[122:123], v[216:217] op_sel_hi:[1,0]
	v_exp_f32_e32 v192, v192
	v_exp_f32_e32 v193, v193
	v_exp_f32_e32 v194, v194
	v_exp_f32_e32 v195, v195
	v_exp_f32_e32 v196, v196
	v_exp_f32_e32 v197, v197
	v_exp_f32_e32 v198, v198
	v_exp_f32_e32 v199, v199
	v_pk_add_f32 v[192:193], v[192:193], 1.0 op_sel_hi:[1,0]
	v_pk_add_f32 v[194:195], v[194:195], 1.0 op_sel_hi:[1,0]
	v_pk_add_f32 v[196:197], v[196:197], 1.0 op_sel_hi:[1,0]
	v_pk_add_f32 v[198:199], v[198:199], 1.0 op_sel_hi:[1,0]
	v_rcp_f32_e32 v192, v192
	v_rcp_f32_e32 v193, v193
	v_rcp_f32_e32 v194, v194
	v_rcp_f32_e32 v195, v195
	v_rcp_f32_e32 v196, v196
	v_rcp_f32_e32 v197, v197
	v_rcp_f32_e32 v198, v198
	v_rcp_f32_e32 v199, v199
	v_pk_mul_f32 v[124:125], v[124:125], v[192:193]
	v_pk_mul_f32 v[126:127], v[126:127], v[194:195]
	v_pk_mul_f32 v[120:121], v[120:121], v[196:197]
	v_pk_mul_f32 v[122:123], v[122:123], v[198:199]
	v_cvt_pk_bf16_f32 v238, v124, v125
	v_cvt_pk_bf16_f32 v239, v126, v127
	v_cvt_pk_bf16_f32 v240, v120, v121
	v_cvt_pk_bf16_f32 v241, v122, v123
	global_store_dwordx4 v[190:191], v[238:241], off
	v_pk_fma_f32 v[116:117], v[116:117], v[202:203], v[28:29] op_sel_hi:[1,0,1]
	v_pk_fma_f32 v[118:119], v[118:119], v[202:203], v[30:31] op_sel_hi:[1,0,1]
	v_pk_fma_f32 v[112:113], v[112:113], v[202:203], v[24:25] op_sel_hi:[1,0,1]
	v_pk_fma_f32 v[114:115], v[114:115], v[202:203], v[26:27] op_sel_hi:[1,0,1]
	v_pk_mul_f32 v[192:193], v[116:117], v[216:217] op_sel_hi:[1,0]
	v_pk_mul_f32 v[194:195], v[118:119], v[216:217] op_sel_hi:[1,0]
; __device__ __forceinline__ unsigned cvt_pk_bf16(float lo, float hi) { unsigned r; asm volatile("v_cvt_pk_bf16_f32 %0, %1, %2" : "=v"(r) : "v"(lo), "v"(hi)); return r; }
; __device__ __forceinline__ float silu_f(float g) { return g * __builtin_amdgcn_rcpf(1.0f + __expf(-g)); }
; __device__ __forceinline__ float sigm_f(float g) { return __builtin_amdgcn_rcpf(1.0f + __expf(-g)); }
;     __device__ __forceinline__ void operator()(const f32x4 (&acc)[2][2][4][2], const Unit& u, int wr, int wc, int fr, int fq) const {
;     ...
;             for (int m = 0; m < 4; ++m) { const int row = row0 + ai * HALF + m * 16;
;                 const float rs = __builtin_amdgcn_rsqf(ssq[row] * (1.0f / 1024.0f) + 1e-6f);
;                 bf16_t* rowp = O + (size_t)row * 4224 + col0;
; #pragma unroll
;                 for (int bj = 0; bj < 2; ++bj) { f32x4 v0 = acc[ai][bj][m][0] * rs + sv[bj][0], v1 = acc[ai][bj][m][1] * rs + sv[bj][1];
;                     if (mode == 1) {
; #pragma unroll
;                         for (int e = 0; e < 4; ++e) { v0[e] = silu_f(v0[e]); v1[e] = silu_f(v1[e]); }
;                     } else if (mode == 2) {
; #pragma unroll
;                         for (int e = 0; e < 4; ++e) { v0[e] = sigm_f(v0[e]); v1[e] = sigm_f(v1[e]); }
;                     }
;                     u32x4 w; w.x = cvt_pk_bf16(v0[0], v0[1]); w.y = cvt_pk_bf16(v0[2], v0[3]); w.z = cvt_pk_bf16(v1[0], v1[1]); w.w = cvt_pk_bf16(v1[2], v1[3]);
;                     *(u32x4*)(rowp + bj * HALF) = w; } }
	v_pk_mul_f32 v[196:197], v[112:113], v[216:217] op_sel_hi:[1,0]
	v_pk_mul_f32 v[198:199], v[114:115], v[216:217] op_sel_hi:[1,0]
	v_exp_f32_e32 v192, v192
	v_exp_f32_e32 v193, v193
	v_exp_f32_e32 v194, v194
	v_exp_f32_e32 v195, v195
	v_exp_f32_e32 v196, v196
	v_exp_f32_e32 v197, v197
	v_exp_f32_e32 v198, v198
	v_exp_f32_e32 v199, v199
	v_pk_add_f32 v[192:193], v[192:193], 1.0 op_sel_hi:[1,0]
	v_pk_add_f32 v[194:195], v[194:195], 1.0 op_sel_hi:[1,0]
	v_pk_add_f32 v[196:197], v[196:197], 1.0 op_sel_hi:[1,0]
	v_pk_add_f32 v[198:199], v[198:199], 1.0 op_sel_hi:[1,0]
	v_rcp_f32_e32 v192, v192
	v_rcp_f32_e32 v193, v193
	v_rcp_f32_e32 v194, v194
	v_rcp_f32_e32 v195, v195
	v_rcp_f32_e32 v196, v196
	v_rcp_f32_e32 v197, v197
	v_rcp_f32_e32 v198, v198
	v_rcp_f32_e32 v199, v199
	v_pk_mul_f32 v[116:117], v[116:117], v[192:193]
	v_pk_mul_f32 v[118:119], v[118:119], v[194:195]
	v_pk_mul_f32 v[112:113], v[112:113], v[196:197]
	v_pk_mul_f32 v[114:115], v[114:115], v[198:199]
	v_cvt_pk_bf16_f32 v218, v116, v117
	v_cvt_pk_bf16_f32 v219, v118, v119
	v_cvt_pk_bf16_f32 v220, v112, v113
	v_cvt_pk_bf16_f32 v221, v114, v115
	global_store_dwordx4 v[190:191], v[218:221], off offset:256
	v_or_b32_e32 v190, 32, v156
	v_mov_b64_e32 v[192:193], s[12:13]
	v_mad_i64_i32 v[190:191], s[0:1], v190, s66, v[192:193]
	v_lshl_add_u64 v[190:191], v[154:155], 1, v[190:191]
	v_pk_fma_f32 v[108:109], v[108:109], v[204:205], v[44:45] op_sel_hi:[1,0,1]
	v_pk_fma_f32 v[110:111], v[110:111], v[204:205], v[46:47] op_sel_hi:[1,0,1]
	v_pk_fma_f32 v[104:105], v[104:105], v[204:205], v[40:41] op_sel_hi:[1,0,1]
	v_pk_fma_f32 v[106:107], v[106:107], v[204:205], v[42:43] op_sel_hi:[1,0,1]
	v_pk_mul_f32 v[192:193], v[108:109], v[216:217] op_sel_hi:[1,0]
	v_pk_mul_f32 v[194:195], v[110:111], v[216:217] op_sel_hi:[1,0]
	v_pk_mul_f32 v[196:197], v[104:105], v[216:217] op_sel_hi:[1,0]
	v_pk_mul_f32 v[198:199], v[106:107], v[216:217] op_sel_hi:[1,0]
	v_exp_f32_e32 v192, v192
	v_exp_f32_e32 v193, v193
	v_exp_f32_e32 v194, v194
	v_exp_f32_e32 v195, v195
	v_exp_f32_e32 v196, v196
	v_exp_f32_e32 v197, v197
	v_exp_f32_e32 v198, v198
	v_exp_f32_e32 v199, v199
	v_pk_add_f32 v[192:193], v[192:193], 1.0 op_sel_hi:[1,0]
	v_pk_add_f32 v[194:195], v[194:195], 1.0 op_sel_hi:[1,0]
	v_pk_add_f32 v[196:197], v[196:197], 1.0 op_sel_hi:[1,0]
	v_pk_add_f32 v[198:199], v[198:199], 1.0 op_sel_hi:[1,0]
	v_rcp_f32_e32 v192, v192
	v_rcp_f32_e32 v193, v193
	v_rcp_f32_e32 v194, v194
	v_rcp_f32_e32 v195, v195
	v_rcp_f32_e32 v196, v196
	v_rcp_f32_e32 v197, v197
	v_rcp_f32_e32 v198, v198
	v_rcp_f32_e32 v199, v199
	v_pk_mul_f32 v[108:109], v[108:109], v[192:193]
	v_pk_mul_f32 v[110:111], v[110:111], v[194:195]
	v_pk_mul_f32 v[104:105], v[104:105], v[196:197]
	v_pk_mul_f32 v[106:107], v[106:107], v[198:199]
	v_cvt_pk_bf16_f32 v238, v108, v109
	v_cvt_pk_bf16_f32 v239, v110, v111
	v_cvt_pk_bf16_f32 v240, v104, v105
	v_cvt_pk_bf16_f32 v241, v106, v107
	global_store_dwordx4 v[190:191], v[238:241], off
	v_pk_fma_f32 v[100:101], v[100:101], v[204:205], v[28:29] op_sel_hi:[1,0,1]
	v_pk_fma_f32 v[102:103], v[102:103], v[204:205], v[30:31] op_sel_hi:[1,0,1]
	v_pk_fma_f32 v[96:97], v[96:97], v[204:205], v[24:25] op_sel_hi:[1,0,1]
	v_pk_fma_f32 v[98:99], v[98:99], v[204:205], v[26:27] op_sel_hi:[1,0,1]
	v_pk_mul_f32 v[192:193], v[100:101], v[216:217] op_sel_hi:[1,0]
	v_pk_mul_f32 v[194:195], v[102:103], v[216:217] op_sel_hi:[1,0]
	v_pk_mul_f32 v[196:197], v[96:97], v[216:217] op_sel_hi:[1,0]
	v_pk_mul_f32 v[198:199], v[98:99], v[216:217] op_sel_hi:[1,0]
	v_exp_f32_e32 v192, v192
	v_exp_f32_e32 v193, v193
	v_exp_f32_e32 v194, v194
	v_exp_f32_e32 v195, v195
	v_exp_f32_e32 v196, v196
	v_exp_f32_e32 v197, v197
	v_exp_f32_e32 v198, v198
	v_exp_f32_e32 v199, v199
	v_pk_add_f32 v[192:193], v[192:193], 1.0 op_sel_hi:[1,0]
	v_pk_add_f32 v[194:195], v[194:195], 1.0 op_sel_hi:[1,0]
	v_pk_add_f32 v[196:197], v[196:197], 1.0 op_sel_hi:[1,0]
	v_pk_add_f32 v[198:199], v[198:199], 1.0 op_sel_hi:[1,0]
	v_rcp_f32_e32 v192, v192
	v_rcp_f32_e32 v193, v193
	v_rcp_f32_e32 v194, v194
	v_rcp_f32_e32 v195, v195
	v_rcp_f32_e32 v196, v196
	v_rcp_f32_e32 v197, v197
	v_rcp_f32_e32 v198, v198
	v_rcp_f32_e32 v199, v199
	v_pk_mul_f32 v[100:101], v[100:101], v[192:193]
	v_pk_mul_f32 v[102:103], v[102:103], v[194:195]
	v_pk_mul_f32 v[96:97], v[96:97], v[196:197]
	v_pk_mul_f32 v[98:99], v[98:99], v[198:199]
	v_cvt_pk_bf16_f32 v218, v100, v101
	v_cvt_pk_bf16_f32 v219, v102, v103
	v_cvt_pk_bf16_f32 v220, v96, v97
	v_cvt_pk_bf16_f32 v221, v98, v99
	global_store_dwordx4 v[190:191], v[218:221], off offset:256
	v_or_b32_e32 v190, 48, v156
	v_mov_b64_e32 v[192:193], s[12:13]
	v_mad_i64_i32 v[190:191], s[0:1], v190, s66, v[192:193]
	v_lshl_add_u64 v[190:191], v[154:155], 1, v[190:191]
	v_pk_fma_f32 v[92:93], v[92:93], v[206:207], v[44:45] op_sel_hi:[1,0,1]
	v_pk_fma_f32 v[94:95], v[94:95], v[206:207], v[46:47] op_sel_hi:[1,0,1]
	v_pk_fma_f32 v[88:89], v[88:89], v[206:207], v[40:41] op_sel_hi:[1,0,1]
	v_pk_fma_f32 v[90:91], v[90:91], v[206:207], v[42:43] op_sel_hi:[1,0,1]
	v_pk_mul_f32 v[192:193], v[92:93], v[216:217] op_sel_hi:[1,0]
	v_pk_mul_f32 v[194:195], v[94:95], v[216:217] op_sel_hi:[1,0]
	v_pk_mul_f32 v[196:197], v[88:89], v[216:217] op_sel_hi:[1,0]
	v_pk_mul_f32 v[198:199], v[90:91], v[216:217] op_sel_hi:[1,0]
	v_exp_f32_e32 v192, v192
	v_exp_f32_e32 v193, v193
	v_exp_f32_e32 v194, v194
	v_exp_f32_e32 v195, v195
	v_exp_f32_e32 v196, v196
	v_exp_f32_e32 v197, v197
	v_exp_f32_e32 v198, v198
	v_exp_f32_e32 v199, v199
	v_pk_add_f32 v[192:193], v[192:193], 1.0 op_sel_hi:[1,0]
	v_pk_add_f32 v[194:195], v[194:195], 1.0 op_sel_hi:[1,0]
	v_pk_add_f32 v[196:197], v[196:197], 1.0 op_sel_hi:[1,0]
; __device__ __forceinline__ unsigned cvt_pk_bf16(float lo, float hi) { unsigned r; asm volatile("v_cvt_pk_bf16_f32 %0, %1, %2" : "=v"(r) : "v"(lo), "v"(hi)); return r; }
; __device__ __forceinline__ float silu_f(float g) { return g * __builtin_amdgcn_rcpf(1.0f + __expf(-g)); }
; __device__ __forceinline__ float sigm_f(float g) { return __builtin_amdgcn_rcpf(1.0f + __expf(-g)); }
;     __device__ __forceinline__ void operator()(const f32x4 (&acc)[2][2][4][2], const Unit& u, int wr, int wc, int fr, int fq) const {
;     ...
;             for (int m = 0; m < 4; ++m) { const int row = row0 + ai * HALF + m * 16;
;                 const float rs = __builtin_amdgcn_rsqf(ssq[row] * (1.0f / 1024.0f) + 1e-6f);
;                 bf16_t* rowp = O + (size_t)row * 4224 + col0;
; #pragma unroll
;                 for (int bj = 0; bj < 2; ++bj) { f32x4 v0 = acc[ai][bj][m][0] * rs + sv[bj][0], v1 = acc[ai][bj][m][1] * rs + sv[bj][1];
;                     if (mode == 1) {
; #pragma unroll
;                         for (int e = 0; e < 4; ++e) { v0[e] = silu_f(v0[e]); v1[e] = silu_f(v1[e]); }
;                     } else if (mode == 2) {
; #pragma unroll
;                         for (int e = 0; e < 4; ++e) { v0[e] = sigm_f(v0[e]); v1[e] = sigm_f(v1[e]); }
;                     }
;                     u32x4 w; w.x = cvt_pk_bf16(v0[0], v0[1]); w.y = cvt_pk_bf16(v0[2], v0[3]); w.z = cvt_pk_bf16(v1[0], v1[1]); w.w = cvt_pk_bf16(v1[2], v1[3]);
;                     *(u32x4*)(rowp + bj * HALF) = w; } }
	v_pk_add_f32 v[198:199], v[198:199], 1.0 op_sel_hi:[1,0]
	v_rcp_f32_e32 v192, v192
	v_rcp_f32_e32 v193, v193
	v_rcp_f32_e32 v194, v194
	v_rcp_f32_e32 v195, v195
	v_rcp_f32_e32 v196, v196
	v_rcp_f32_e32 v197, v197
	v_rcp_f32_e32 v198, v198
	v_rcp_f32_e32 v199, v199
	v_pk_mul_f32 v[92:93], v[92:93], v[192:193]
	v_pk_mul_f32 v[94:95], v[94:95], v[194:195]
	v_pk_mul_f32 v[88:89], v[88:89], v[196:197]
	v_pk_mul_f32 v[90:91], v[90:91], v[198:199]
	v_cvt_pk_bf16_f32 v238, v92, v93
	v_cvt_pk_bf16_f32 v239, v94, v95
	v_cvt_pk_bf16_f32 v240, v88, v89
	v_cvt_pk_bf16_f32 v241, v90, v91
	global_store_dwordx4 v[190:191], v[238:241], off
	v_pk_fma_f32 v[84:85], v[84:85], v[206:207], v[28:29] op_sel_hi:[1,0,1]
	v_pk_fma_f32 v[86:87], v[86:87], v[206:207], v[30:31] op_sel_hi:[1,0,1]
	v_pk_fma_f32 v[80:81], v[80:81], v[206:207], v[24:25] op_sel_hi:[1,0,1]
	v_pk_fma_f32 v[82:83], v[82:83], v[206:207], v[26:27] op_sel_hi:[1,0,1]
	v_pk_mul_f32 v[192:193], v[84:85], v[216:217] op_sel_hi:[1,0]
	v_pk_mul_f32 v[194:195], v[86:87], v[216:217] op_sel_hi:[1,0]
	v_pk_mul_f32 v[196:197], v[80:81], v[216:217] op_sel_hi:[1,0]
	v_pk_mul_f32 v[198:199], v[82:83], v[216:217] op_sel_hi:[1,0]
	v_exp_f32_e32 v192, v192
	v_exp_f32_e32 v193, v193
	v_exp_f32_e32 v194, v194
	v_exp_f32_e32 v195, v195
	v_exp_f32_e32 v196, v196
	v_exp_f32_e32 v197, v197
	v_exp_f32_e32 v198, v198
	v_exp_f32_e32 v199, v199
	v_pk_add_f32 v[192:193], v[192:193], 1.0 op_sel_hi:[1,0]
	v_pk_add_f32 v[194:195], v[194:195], 1.0 op_sel_hi:[1,0]
	v_pk_add_f32 v[196:197], v[196:197], 1.0 op_sel_hi:[1,0]
	v_pk_add_f32 v[198:199], v[198:199], 1.0 op_sel_hi:[1,0]
	v_rcp_f32_e32 v192, v192
	v_rcp_f32_e32 v193, v193
	v_rcp_f32_e32 v194, v194
	v_rcp_f32_e32 v195, v195
	v_rcp_f32_e32 v196, v196
	v_rcp_f32_e32 v197, v197
	v_rcp_f32_e32 v198, v198
	v_rcp_f32_e32 v199, v199
	v_pk_mul_f32 v[84:85], v[84:85], v[192:193]
	v_pk_mul_f32 v[86:87], v[86:87], v[194:195]
	v_pk_mul_f32 v[80:81], v[80:81], v[196:197]
	v_pk_mul_f32 v[82:83], v[82:83], v[198:199]
	v_cvt_pk_bf16_f32 v218, v84, v85
	v_cvt_pk_bf16_f32 v219, v86, v87
	v_cvt_pk_bf16_f32 v220, v80, v81
	v_cvt_pk_bf16_f32 v221, v82, v83
	global_store_dwordx4 v[190:191], v[218:221], off offset:256
	v_add_u32_e32 v190, 0x80, v156
	v_mov_b64_e32 v[192:193], s[12:13]
	v_mad_i64_i32 v[190:191], s[0:1], v190, s66, v[192:193]
	v_lshl_add_u64 v[190:191], v[154:155], 1, v[190:191]
	v_pk_fma_f32 v[76:77], v[76:77], v[208:209], v[44:45] op_sel_hi:[1,0,1]
	v_pk_fma_f32 v[78:79], v[78:79], v[208:209], v[46:47] op_sel_hi:[1,0,1]
	v_pk_fma_f32 v[72:73], v[72:73], v[208:209], v[40:41] op_sel_hi:[1,0,1]
	v_pk_fma_f32 v[74:75], v[74:75], v[208:209], v[42:43] op_sel_hi:[1,0,1]
	v_pk_mul_f32 v[192:193], v[76:77], v[216:217] op_sel_hi:[1,0]
	v_pk_mul_f32 v[194:195], v[78:79], v[216:217] op_sel_hi:[1,0]
	v_pk_mul_f32 v[196:197], v[72:73], v[216:217] op_sel_hi:[1,0]
	v_pk_mul_f32 v[198:199], v[74:75], v[216:217] op_sel_hi:[1,0]
	v_exp_f32_e32 v192, v192
	v_exp_f32_e32 v193, v193
	v_exp_f32_e32 v194, v194
	v_exp_f32_e32 v195, v195
	v_exp_f32_e32 v196, v196
	v_exp_f32_e32 v197, v197
	v_exp_f32_e32 v198, v198
	v_exp_f32_e32 v199, v199
	v_pk_add_f32 v[192:193], v[192:193], 1.0 op_sel_hi:[1,0]
	v_pk_add_f32 v[194:195], v[194:195], 1.0 op_sel_hi:[1,0]
	v_pk_add_f32 v[196:197], v[196:197], 1.0 op_sel_hi:[1,0]
	v_pk_add_f32 v[198:199], v[198:199], 1.0 op_sel_hi:[1,0]
	v_rcp_f32_e32 v192, v192
	v_rcp_f32_e32 v193, v193
	v_rcp_f32_e32 v194, v194
	v_rcp_f32_e32 v195, v195
	v_rcp_f32_e32 v196, v196
	v_rcp_f32_e32 v197, v197
	v_rcp_f32_e32 v198, v198
	v_rcp_f32_e32 v199, v199
	v_pk_mul_f32 v[76:77], v[76:77], v[192:193]
	v_pk_mul_f32 v[78:79], v[78:79], v[194:195]
	v_pk_mul_f32 v[72:73], v[72:73], v[196:197]
	v_pk_mul_f32 v[74:75], v[74:75], v[198:199]
	v_cvt_pk_bf16_f32 v238, v76, v77
	v_cvt_pk_bf16_f32 v239, v78, v79
	v_cvt_pk_bf16_f32 v240, v72, v73
	v_cvt_pk_bf16_f32 v241, v74, v75
	global_store_dwordx4 v[190:191], v[238:241], off
	v_pk_fma_f32 v[68:69], v[68:69], v[208:209], v[28:29] op_sel_hi:[1,0,1]
	v_pk_fma_f32 v[70:71], v[70:71], v[208:209], v[30:31] op_sel_hi:[1,0,1]
	v_pk_fma_f32 v[64:65], v[64:65], v[208:209], v[24:25] op_sel_hi:[1,0,1]
	v_pk_fma_f32 v[66:67], v[66:67], v[208:209], v[26:27] op_sel_hi:[1,0,1]
	v_pk_mul_f32 v[192:193], v[68:69], v[216:217] op_sel_hi:[1,0]
	v_pk_mul_f32 v[194:195], v[70:71], v[216:217] op_sel_hi:[1,0]
	v_pk_mul_f32 v[196:197], v[64:65], v[216:217] op_sel_hi:[1,0]
	v_pk_mul_f32 v[198:199], v[66:67], v[216:217] op_sel_hi:[1,0]
	v_exp_f32_e32 v192, v192
	v_exp_f32_e32 v193, v193
	v_exp_f32_e32 v194, v194
	v_exp_f32_e32 v195, v195
	v_exp_f32_e32 v196, v196
	v_exp_f32_e32 v197, v197
	v_exp_f32_e32 v198, v198
	v_exp_f32_e32 v199, v199
	v_pk_add_f32 v[192:193], v[192:193], 1.0 op_sel_hi:[1,0]
	v_pk_add_f32 v[194:195], v[194:195], 1.0 op_sel_hi:[1,0]
	v_pk_add_f32 v[196:197], v[196:197], 1.0 op_sel_hi:[1,0]
	v_pk_add_f32 v[198:199], v[198:199], 1.0 op_sel_hi:[1,0]
	v_rcp_f32_e32 v192, v192
	v_rcp_f32_e32 v193, v193
	v_rcp_f32_e32 v194, v194
	v_rcp_f32_e32 v195, v195
	v_rcp_f32_e32 v196, v196
	v_rcp_f32_e32 v197, v197
	v_rcp_f32_e32 v198, v198
	v_rcp_f32_e32 v199, v199
	v_pk_mul_f32 v[68:69], v[68:69], v[192:193]
	v_pk_mul_f32 v[70:71], v[70:71], v[194:195]
	v_pk_mul_f32 v[64:65], v[64:65], v[196:197]
	v_pk_mul_f32 v[66:67], v[66:67], v[198:199]
	v_cvt_pk_bf16_f32 v218, v68, v69
	v_cvt_pk_bf16_f32 v219, v70, v71
	v_cvt_pk_bf16_f32 v220, v64, v65
	v_cvt_pk_bf16_f32 v221, v66, v67
	global_store_dwordx4 v[190:191], v[218:221], off offset:256
	v_add_u32_e32 v190, 0x90, v156
	v_mov_b64_e32 v[192:193], s[12:13]
	v_mad_i64_i32 v[190:191], s[0:1], v190, s66, v[192:193]
; __device__ __forceinline__ unsigned cvt_pk_bf16(float lo, float hi) { unsigned r; asm volatile("v_cvt_pk_bf16_f32 %0, %1, %2" : "=v"(r) : "v"(lo), "v"(hi)); return r; }
; __device__ __forceinline__ float silu_f(float g) { return g * __builtin_amdgcn_rcpf(1.0f + __expf(-g)); }
; __device__ __forceinline__ float sigm_f(float g) { return __builtin_amdgcn_rcpf(1.0f + __expf(-g)); }
;     __device__ __forceinline__ void operator()(const f32x4 (&acc)[2][2][4][2], const Unit& u, int wr, int wc, int fr, int fq) const {
;     ...
;             for (int m = 0; m < 4; ++m) { const int row = row0 + ai * HALF + m * 16;
;                 const float rs = __builtin_amdgcn_rsqf(ssq[row] * (1.0f / 1024.0f) + 1e-6f);
;                 bf16_t* rowp = O + (size_t)row * 4224 + col0;
; #pragma unroll
;                 for (int bj = 0; bj < 2; ++bj) { f32x4 v0 = acc[ai][bj][m][0] * rs + sv[bj][0], v1 = acc[ai][bj][m][1] * rs + sv[bj][1];
;                     if (mode == 1) {
; #pragma unroll
;                         for (int e = 0; e < 4; ++e) { v0[e] = silu_f(v0[e]); v1[e] = silu_f(v1[e]); }
;                     } else if (mode == 2) {
; #pragma unroll
;                         for (int e = 0; e < 4; ++e) { v0[e] = sigm_f(v0[e]); v1[e] = sigm_f(v1[e]); }
;                     }
;                     u32x4 w; w.x = cvt_pk_bf16(v0[0], v0[1]); w.y = cvt_pk_bf16(v0[2], v0[3]); w.z = cvt_pk_bf16(v1[0], v1[1]); w.w = cvt_pk_bf16(v1[2], v1[3]);
;                     *(u32x4*)(rowp + bj * HALF) = w; } }
	v_lshl_add_u64 v[190:191], v[154:155], 1, v[190:191]
	v_pk_fma_f32 v[60:61], v[60:61], v[210:211], v[44:45] op_sel_hi:[1,0,1]
	v_pk_fma_f32 v[62:63], v[62:63], v[210:211], v[46:47] op_sel_hi:[1,0,1]
	v_pk_fma_f32 v[56:57], v[56:57], v[210:211], v[40:41] op_sel_hi:[1,0,1]
	v_pk_fma_f32 v[58:59], v[58:59], v[210:211], v[42:43] op_sel_hi:[1,0,1]
	v_pk_mul_f32 v[192:193], v[60:61], v[216:217] op_sel_hi:[1,0]
	v_pk_mul_f32 v[194:195], v[62:63], v[216:217] op_sel_hi:[1,0]
	v_pk_mul_f32 v[196:197], v[56:57], v[216:217] op_sel_hi:[1,0]
	v_pk_mul_f32 v[198:199], v[58:59], v[216:217] op_sel_hi:[1,0]
	v_exp_f32_e32 v192, v192
	v_exp_f32_e32 v193, v193
	v_exp_f32_e32 v194, v194
	v_exp_f32_e32 v195, v195
	v_exp_f32_e32 v196, v196
	v_exp_f32_e32 v197, v197
	v_exp_f32_e32 v198, v198
	v_exp_f32_e32 v199, v199
	v_pk_add_f32 v[192:193], v[192:193], 1.0 op_sel_hi:[1,0]
	v_pk_add_f32 v[194:195], v[194:195], 1.0 op_sel_hi:[1,0]
	v_pk_add_f32 v[196:197], v[196:197], 1.0 op_sel_hi:[1,0]
	v_pk_add_f32 v[198:199], v[198:199], 1.0 op_sel_hi:[1,0]
	v_rcp_f32_e32 v192, v192
	v_rcp_f32_e32 v193, v193
	v_rcp_f32_e32 v194, v194
	v_rcp_f32_e32 v195, v195
	v_rcp_f32_e32 v196, v196
	v_rcp_f32_e32 v197, v197
	v_rcp_f32_e32 v198, v198
	v_rcp_f32_e32 v199, v199
	v_pk_mul_f32 v[60:61], v[60:61], v[192:193]
	v_pk_mul_f32 v[62:63], v[62:63], v[194:195]
	v_pk_mul_f32 v[56:57], v[56:57], v[196:197]
	v_pk_mul_f32 v[58:59], v[58:59], v[198:199]
	v_cvt_pk_bf16_f32 v238, v60, v61
	v_cvt_pk_bf16_f32 v239, v62, v63
	v_cvt_pk_bf16_f32 v240, v56, v57
	v_cvt_pk_bf16_f32 v241, v58, v59
	global_store_dwordx4 v[190:191], v[238:241], off
	v_pk_fma_f32 v[52:53], v[52:53], v[210:211], v[28:29] op_sel_hi:[1,0,1]
	v_pk_fma_f32 v[54:55], v[54:55], v[210:211], v[30:31] op_sel_hi:[1,0,1]
	v_pk_fma_f32 v[48:49], v[48:49], v[210:211], v[24:25] op_sel_hi:[1,0,1]
	v_pk_fma_f32 v[50:51], v[50:51], v[210:211], v[26:27] op_sel_hi:[1,0,1]
	v_pk_mul_f32 v[192:193], v[52:53], v[216:217] op_sel_hi:[1,0]
	v_pk_mul_f32 v[194:195], v[54:55], v[216:217] op_sel_hi:[1,0]
	v_pk_mul_f32 v[196:197], v[48:49], v[216:217] op_sel_hi:[1,0]
	v_pk_mul_f32 v[198:199], v[50:51], v[216:217] op_sel_hi:[1,0]
	v_exp_f32_e32 v192, v192
	v_exp_f32_e32 v193, v193
	v_exp_f32_e32 v194, v194
	v_exp_f32_e32 v195, v195
	v_exp_f32_e32 v196, v196
	v_exp_f32_e32 v197, v197
	v_exp_f32_e32 v198, v198
	v_exp_f32_e32 v199, v199
	v_pk_add_f32 v[192:193], v[192:193], 1.0 op_sel_hi:[1,0]
	v_pk_add_f32 v[194:195], v[194:195], 1.0 op_sel_hi:[1,0]
	v_pk_add_f32 v[196:197], v[196:197], 1.0 op_sel_hi:[1,0]
	v_pk_add_f32 v[198:199], v[198:199], 1.0 op_sel_hi:[1,0]
	v_rcp_f32_e32 v192, v192
	v_rcp_f32_e32 v193, v193
	v_rcp_f32_e32 v194, v194
	v_rcp_f32_e32 v195, v195
	v_rcp_f32_e32 v196, v196
	v_rcp_f32_e32 v197, v197
	v_rcp_f32_e32 v198, v198
	v_rcp_f32_e32 v199, v199
	v_pk_mul_f32 v[52:53], v[52:53], v[192:193]
	v_pk_mul_f32 v[54:55], v[54:55], v[194:195]
	v_pk_mul_f32 v[48:49], v[48:49], v[196:197]
	v_pk_mul_f32 v[50:51], v[50:51], v[198:199]
	v_cvt_pk_bf16_f32 v218, v52, v53
	v_cvt_pk_bf16_f32 v219, v54, v55
	v_cvt_pk_bf16_f32 v220, v48, v49
	v_cvt_pk_bf16_f32 v221, v50, v51
	global_store_dwordx4 v[190:191], v[218:221], off offset:256
	v_add_u32_e32 v190, 0xa0, v156
	v_mov_b64_e32 v[192:193], s[12:13]
	v_mad_i64_i32 v[190:191], s[0:1], v190, s66, v[192:193]
	v_lshl_add_u64 v[190:191], v[154:155], 1, v[190:191]
	v_pk_fma_f32 v[36:37], v[36:37], v[212:213], v[44:45] op_sel_hi:[1,0,1]
	v_pk_fma_f32 v[38:39], v[38:39], v[212:213], v[46:47] op_sel_hi:[1,0,1]
	v_pk_fma_f32 v[32:33], v[32:33], v[212:213], v[40:41] op_sel_hi:[1,0,1]
	v_pk_fma_f32 v[34:35], v[34:35], v[212:213], v[42:43] op_sel_hi:[1,0,1]
	v_pk_mul_f32 v[192:193], v[36:37], v[216:217] op_sel_hi:[1,0]
	v_pk_mul_f32 v[194:195], v[38:39], v[216:217] op_sel_hi:[1,0]
	v_pk_mul_f32 v[196:197], v[32:33], v[216:217] op_sel_hi:[1,0]
	v_pk_mul_f32 v[198:199], v[34:35], v[216:217] op_sel_hi:[1,0]
	v_exp_f32_e32 v192, v192
	v_exp_f32_e32 v193, v193
	v_exp_f32_e32 v194, v194
	v_exp_f32_e32 v195, v195
	v_exp_f32_e32 v196, v196
	v_exp_f32_e32 v197, v197
	v_exp_f32_e32 v198, v198
	v_exp_f32_e32 v199, v199
	v_pk_add_f32 v[192:193], v[192:193], 1.0 op_sel_hi:[1,0]
	v_pk_add_f32 v[194:195], v[194:195], 1.0 op_sel_hi:[1,0]
	v_pk_add_f32 v[196:197], v[196:197], 1.0 op_sel_hi:[1,0]
	v_pk_add_f32 v[198:199], v[198:199], 1.0 op_sel_hi:[1,0]
	v_rcp_f32_e32 v192, v192
	v_rcp_f32_e32 v193, v193
	v_rcp_f32_e32 v194, v194
	v_rcp_f32_e32 v195, v195
	v_rcp_f32_e32 v196, v196
	v_rcp_f32_e32 v197, v197
	v_rcp_f32_e32 v198, v198
	v_rcp_f32_e32 v199, v199
	v_pk_mul_f32 v[36:37], v[36:37], v[192:193]
	v_pk_mul_f32 v[38:39], v[38:39], v[194:195]
	v_pk_mul_f32 v[32:33], v[32:33], v[196:197]
	v_pk_mul_f32 v[34:35], v[34:35], v[198:199]
	v_cvt_pk_bf16_f32 v238, v36, v37
	v_cvt_pk_bf16_f32 v239, v38, v39
	v_cvt_pk_bf16_f32 v240, v32, v33
	v_cvt_pk_bf16_f32 v241, v34, v35
	global_store_dwordx4 v[190:191], v[238:241], off
	v_pk_fma_f32 v[20:21], v[20:21], v[212:213], v[28:29] op_sel_hi:[1,0,1]
	v_pk_fma_f32 v[22:23], v[22:23], v[212:213], v[30:31] op_sel_hi:[1,0,1]
	v_pk_fma_f32 v[16:17], v[16:17], v[212:213], v[24:25] op_sel_hi:[1,0,1]
	v_pk_fma_f32 v[18:19], v[18:19], v[212:213], v[26:27] op_sel_hi:[1,0,1]
	v_pk_mul_f32 v[192:193], v[20:21], v[216:217] op_sel_hi:[1,0]
	v_pk_mul_f32 v[194:195], v[22:23], v[216:217] op_sel_hi:[1,0]
	v_pk_mul_f32 v[196:197], v[16:17], v[216:217] op_sel_hi:[1,0]
	v_pk_mul_f32 v[198:199], v[18:19], v[216:217] op_sel_hi:[1,0]
	v_exp_f32_e32 v192, v192
	v_exp_f32_e32 v193, v193
	v_exp_f32_e32 v194, v194
	v_exp_f32_e32 v195, v195
	v_exp_f32_e32 v196, v196
	v_exp_f32_e32 v197, v197
	v_exp_f32_e32 v198, v198
; __device__ __forceinline__ unsigned cvt_pk_bf16(float lo, float hi) { unsigned r; asm volatile("v_cvt_pk_bf16_f32 %0, %1, %2" : "=v"(r) : "v"(lo), "v"(hi)); return r; }
; __device__ __forceinline__ float silu_f(float g) { return g * __builtin_amdgcn_rcpf(1.0f + __expf(-g)); }
; __device__ __forceinline__ float sigm_f(float g) { return __builtin_amdgcn_rcpf(1.0f + __expf(-g)); }
;     __device__ __forceinline__ void operator()(const f32x4 (&acc)[2][2][4][2], const Unit& u, int wr, int wc, int fr, int fq) const {
;     ...
;             for (int m = 0; m < 4; ++m) { const int row = row0 + ai * HALF + m * 16;
;                 const float rs = __builtin_amdgcn_rsqf(ssq[row] * (1.0f / 1024.0f) + 1e-6f);
;                 bf16_t* rowp = O + (size_t)row * 4224 + col0;
; #pragma unroll
;                 for (int bj = 0; bj < 2; ++bj) { f32x4 v0 = acc[ai][bj][m][0] * rs + sv[bj][0], v1 = acc[ai][bj][m][1] * rs + sv[bj][1];
;                     if (mode == 1) {
; #pragma unroll
;                         for (int e = 0; e < 4; ++e) { v0[e] = silu_f(v0[e]); v1[e] = silu_f(v1[e]); }
;                     } else if (mode == 2) {
; #pragma unroll
;                         for (int e = 0; e < 4; ++e) { v0[e] = sigm_f(v0[e]); v1[e] = sigm_f(v1[e]); }
;                     }
;                     u32x4 w; w.x = cvt_pk_bf16(v0[0], v0[1]); w.y = cvt_pk_bf16(v0[2], v0[3]); w.z = cvt_pk_bf16(v1[0], v1[1]); w.w = cvt_pk_bf16(v1[2], v1[3]);
;                     *(u32x4*)(rowp + bj * HALF) = w; } }
	v_exp_f32_e32 v199, v199
	v_pk_add_f32 v[192:193], v[192:193], 1.0 op_sel_hi:[1,0]
	v_pk_add_f32 v[194:195], v[194:195], 1.0 op_sel_hi:[1,0]
	v_pk_add_f32 v[196:197], v[196:197], 1.0 op_sel_hi:[1,0]
	v_pk_add_f32 v[198:199], v[198:199], 1.0 op_sel_hi:[1,0]
	v_rcp_f32_e32 v192, v192
	v_rcp_f32_e32 v193, v193
	v_rcp_f32_e32 v194, v194
	v_rcp_f32_e32 v195, v195
	v_rcp_f32_e32 v196, v196
	v_rcp_f32_e32 v197, v197
	v_rcp_f32_e32 v198, v198
	v_rcp_f32_e32 v199, v199
	v_pk_mul_f32 v[20:21], v[20:21], v[192:193]
	v_pk_mul_f32 v[22:23], v[22:23], v[194:195]
	v_pk_mul_f32 v[16:17], v[16:17], v[196:197]
	v_pk_mul_f32 v[18:19], v[18:19], v[198:199]
	v_cvt_pk_bf16_f32 v218, v20, v21
	v_cvt_pk_bf16_f32 v219, v22, v23
	v_cvt_pk_bf16_f32 v220, v16, v17
	v_cvt_pk_bf16_f32 v221, v18, v19
	global_store_dwordx4 v[190:191], v[218:221], off offset:256
	v_add_u32_e32 v190, 0xb0, v156
	v_mov_b64_e32 v[192:193], s[12:13]
	v_mad_i64_i32 v[190:191], s[0:1], v190, s66, v[192:193]
	v_lshl_add_u64 v[190:191], v[154:155], 1, v[190:191]
	v_pk_fma_f32 v[12:13], v[12:13], v[214:215], v[44:45] op_sel_hi:[1,0,1]
	v_pk_fma_f32 v[14:15], v[14:15], v[214:215], v[46:47] op_sel_hi:[1,0,1]
	v_pk_fma_f32 v[8:9], v[8:9], v[214:215], v[40:41] op_sel_hi:[1,0,1]
	v_pk_fma_f32 v[10:11], v[10:11], v[214:215], v[42:43] op_sel_hi:[1,0,1]
	v_pk_mul_f32 v[192:193], v[12:13], v[216:217] op_sel_hi:[1,0]
	v_pk_mul_f32 v[194:195], v[14:15], v[216:217] op_sel_hi:[1,0]
	v_pk_mul_f32 v[196:197], v[8:9], v[216:217] op_sel_hi:[1,0]
	v_pk_mul_f32 v[198:199], v[10:11], v[216:217] op_sel_hi:[1,0]
	v_exp_f32_e32 v192, v192
	v_exp_f32_e32 v193, v193
	v_exp_f32_e32 v194, v194
	v_exp_f32_e32 v195, v195
	v_exp_f32_e32 v196, v196
	v_exp_f32_e32 v197, v197
	v_exp_f32_e32 v198, v198
	v_exp_f32_e32 v199, v199
	v_pk_add_f32 v[192:193], v[192:193], 1.0 op_sel_hi:[1,0]
	v_pk_add_f32 v[194:195], v[194:195], 1.0 op_sel_hi:[1,0]
	v_pk_add_f32 v[196:197], v[196:197], 1.0 op_sel_hi:[1,0]
	v_pk_add_f32 v[198:199], v[198:199], 1.0 op_sel_hi:[1,0]
	v_rcp_f32_e32 v192, v192
	v_rcp_f32_e32 v193, v193
	v_rcp_f32_e32 v194, v194
	v_rcp_f32_e32 v195, v195
	v_rcp_f32_e32 v196, v196
	v_rcp_f32_e32 v197, v197
	v_rcp_f32_e32 v198, v198
	v_rcp_f32_e32 v199, v199
	v_pk_mul_f32 v[12:13], v[12:13], v[192:193]
	v_pk_mul_f32 v[14:15], v[14:15], v[194:195]
	v_pk_mul_f32 v[8:9], v[8:9], v[196:197]
	v_pk_mul_f32 v[10:11], v[10:11], v[198:199]
	v_cvt_pk_bf16_f32 v238, v12, v13
	v_cvt_pk_bf16_f32 v239, v14, v15
	v_cvt_pk_bf16_f32 v240, v8, v9
	v_cvt_pk_bf16_f32 v241, v10, v11
	global_store_dwordx4 v[190:191], v[238:241], off
	v_pk_fma_f32 v[4:5], v[4:5], v[214:215], v[28:29] op_sel_hi:[1,0,1]
	v_pk_fma_f32 v[6:7], v[6:7], v[214:215], v[30:31] op_sel_hi:[1,0,1]
	v_pk_fma_f32 v[0:1], v[0:1], v[214:215], v[24:25] op_sel_hi:[1,0,1]
	v_pk_fma_f32 v[2:3], v[2:3], v[214:215], v[26:27] op_sel_hi:[1,0,1]
	v_pk_mul_f32 v[192:193], v[4:5], v[216:217] op_sel_hi:[1,0]
	v_pk_mul_f32 v[194:195], v[6:7], v[216:217] op_sel_hi:[1,0]
	v_pk_mul_f32 v[196:197], v[0:1], v[216:217] op_sel_hi:[1,0]
	v_pk_mul_f32 v[198:199], v[2:3], v[216:217] op_sel_hi:[1,0]
	v_exp_f32_e32 v192, v192
	v_exp_f32_e32 v193, v193
	v_exp_f32_e32 v194, v194
	v_exp_f32_e32 v195, v195
	v_exp_f32_e32 v196, v196
	v_exp_f32_e32 v197, v197
	v_exp_f32_e32 v198, v198
	v_exp_f32_e32 v199, v199
	v_pk_add_f32 v[192:193], v[192:193], 1.0 op_sel_hi:[1,0]
	v_pk_add_f32 v[194:195], v[194:195], 1.0 op_sel_hi:[1,0]
	v_pk_add_f32 v[196:197], v[196:197], 1.0 op_sel_hi:[1,0]
	v_pk_add_f32 v[198:199], v[198:199], 1.0 op_sel_hi:[1,0]
	v_rcp_f32_e32 v192, v192
	v_rcp_f32_e32 v193, v193
	v_rcp_f32_e32 v194, v194
	v_rcp_f32_e32 v195, v195
	v_rcp_f32_e32 v196, v196
	v_rcp_f32_e32 v197, v197
	v_rcp_f32_e32 v198, v198
	v_rcp_f32_e32 v199, v199
	v_pk_mul_f32 v[4:5], v[4:5], v[192:193]
	v_pk_mul_f32 v[6:7], v[6:7], v[194:195]
	v_pk_mul_f32 v[0:1], v[0:1], v[196:197]
	v_pk_mul_f32 v[2:3], v[2:3], v[198:199]
	v_cvt_pk_bf16_f32 v218, v4, v5
	v_cvt_pk_bf16_f32 v219, v6, v7
	v_cvt_pk_bf16_f32 v220, v0, v1
	v_cvt_pk_bf16_f32 v221, v2, v3
	global_store_dwordx4 v[190:191], v[218:221], off offset:256
	s_branch .Lpj_done
.Lpj_sigm:
	v_mov_b32_e32 v190, v156
	v_mov_b64_e32 v[192:193], s[12:13]
	v_mad_i64_i32 v[190:191], s[0:1], v190, s66, v[192:193]
	v_lshl_add_u64 v[190:191], v[154:155], 1, v[190:191]
	v_pk_fma_f32 v[140:141], v[140:141], v[200:201], v[44:45] op_sel_hi:[1,0,1]
	v_pk_fma_f32 v[142:143], v[142:143], v[200:201], v[46:47] op_sel_hi:[1,0,1]
	v_pk_fma_f32 v[136:137], v[136:137], v[200:201], v[40:41] op_sel_hi:[1,0,1]
	v_pk_fma_f32 v[138:139], v[138:139], v[200:201], v[42:43] op_sel_hi:[1,0,1]
	v_pk_mul_f32 v[192:193], v[140:141], v[216:217] op_sel_hi:[1,0]
	v_pk_mul_f32 v[194:195], v[142:143], v[216:217] op_sel_hi:[1,0]
	v_pk_mul_f32 v[196:197], v[136:137], v[216:217] op_sel_hi:[1,0]
	v_pk_mul_f32 v[198:199], v[138:139], v[216:217] op_sel_hi:[1,0]
	v_exp_f32_e32 v192, v192
	v_exp_f32_e32 v193, v193
	v_exp_f32_e32 v194, v194
	v_exp_f32_e32 v195, v195
	v_exp_f32_e32 v196, v196
	v_exp_f32_e32 v197, v197
	v_exp_f32_e32 v198, v198
	v_exp_f32_e32 v199, v199
	v_pk_add_f32 v[192:193], v[192:193], 1.0 op_sel_hi:[1,0]
	v_pk_add_f32 v[194:195], v[194:195], 1.0 op_sel_hi:[1,0]
	v_pk_add_f32 v[196:197], v[196:197], 1.0 op_sel_hi:[1,0]
	v_pk_add_f32 v[198:199], v[198:199], 1.0 op_sel_hi:[1,0]
	v_rcp_f32_e32 v192, v192
	v_rcp_f32_e32 v193, v193
	v_rcp_f32_e32 v194, v194
	v_rcp_f32_e32 v195, v195
	v_rcp_f32_e32 v196, v196
	v_rcp_f32_e32 v197, v197
	v_rcp_f32_e32 v198, v198
	v_rcp_f32_e32 v199, v199
	v_cvt_pk_bf16_f32 v238, v192, v193
	v_cvt_pk_bf16_f32 v239, v194, v195
	v_cvt_pk_bf16_f32 v240, v196, v197
	v_cvt_pk_bf16_f32 v241, v198, v199
; __device__ __forceinline__ unsigned cvt_pk_bf16(float lo, float hi) { unsigned r; asm volatile("v_cvt_pk_bf16_f32 %0, %1, %2" : "=v"(r) : "v"(lo), "v"(hi)); return r; }
; __device__ __forceinline__ float silu_f(float g) { return g * __builtin_amdgcn_rcpf(1.0f + __expf(-g)); }
; __device__ __forceinline__ float sigm_f(float g) { return __builtin_amdgcn_rcpf(1.0f + __expf(-g)); }
;     __device__ __forceinline__ void operator()(const f32x4 (&acc)[2][2][4][2], const Unit& u, int wr, int wc, int fr, int fq) const {
;     ...
;             for (int m = 0; m < 4; ++m) { const int row = row0 + ai * HALF + m * 16;
;                 const float rs = __builtin_amdgcn_rsqf(ssq[row] * (1.0f / 1024.0f) + 1e-6f);
;                 bf16_t* rowp = O + (size_t)row * 4224 + col0;
; #pragma unroll
;                 for (int bj = 0; bj < 2; ++bj) { f32x4 v0 = acc[ai][bj][m][0] * rs + sv[bj][0], v1 = acc[ai][bj][m][1] * rs + sv[bj][1];
;                     if (mode == 1) {
; #pragma unroll
;                         for (int e = 0; e < 4; ++e) { v0[e] = silu_f(v0[e]); v1[e] = silu_f(v1[e]); }
;                     } else if (mode == 2) {
; #pragma unroll
;                         for (int e = 0; e < 4; ++e) { v0[e] = sigm_f(v0[e]); v1[e] = sigm_f(v1[e]); }
;                     }
;                     u32x4 w; w.x = cvt_pk_bf16(v0[0], v0[1]); w.y = cvt_pk_bf16(v0[2], v0[3]); w.z = cvt_pk_bf16(v1[0], v1[1]); w.w = cvt_pk_bf16(v1[2], v1[3]);
;                     *(u32x4*)(rowp + bj * HALF) = w; } }
	global_store_dwordx4 v[190:191], v[238:241], off
	v_pk_fma_f32 v[132:133], v[132:133], v[200:201], v[28:29] op_sel_hi:[1,0,1]
	v_pk_fma_f32 v[134:135], v[134:135], v[200:201], v[30:31] op_sel_hi:[1,0,1]
	v_pk_fma_f32 v[128:129], v[128:129], v[200:201], v[24:25] op_sel_hi:[1,0,1]
	v_pk_fma_f32 v[130:131], v[130:131], v[200:201], v[26:27] op_sel_hi:[1,0,1]
	v_pk_mul_f32 v[192:193], v[132:133], v[216:217] op_sel_hi:[1,0]
	v_pk_mul_f32 v[194:195], v[134:135], v[216:217] op_sel_hi:[1,0]
	v_pk_mul_f32 v[196:197], v[128:129], v[216:217] op_sel_hi:[1,0]
	v_pk_mul_f32 v[198:199], v[130:131], v[216:217] op_sel_hi:[1,0]
	v_exp_f32_e32 v192, v192
	v_exp_f32_e32 v193, v193
	v_exp_f32_e32 v194, v194
	v_exp_f32_e32 v195, v195
	v_exp_f32_e32 v196, v196
	v_exp_f32_e32 v197, v197
	v_exp_f32_e32 v198, v198
	v_exp_f32_e32 v199, v199
	v_pk_add_f32 v[192:193], v[192:193], 1.0 op_sel_hi:[1,0]
	v_pk_add_f32 v[194:195], v[194:195], 1.0 op_sel_hi:[1,0]
	v_pk_add_f32 v[196:197], v[196:197], 1.0 op_sel_hi:[1,0]
	v_pk_add_f32 v[198:199], v[198:199], 1.0 op_sel_hi:[1,0]
	v_rcp_f32_e32 v192, v192
	v_rcp_f32_e32 v193, v193
	v_rcp_f32_e32 v194, v194
	v_rcp_f32_e32 v195, v195
	v_rcp_f32_e32 v196, v196
	v_rcp_f32_e32 v197, v197
	v_rcp_f32_e32 v198, v198
	v_rcp_f32_e32 v199, v199
	v_cvt_pk_bf16_f32 v218, v192, v193
	v_cvt_pk_bf16_f32 v219, v194, v195
	v_cvt_pk_bf16_f32 v220, v196, v197
	v_cvt_pk_bf16_f32 v221, v198, v199
	global_store_dwordx4 v[190:191], v[218:221], off offset:256
	v_or_b32_e32 v190, 16, v156
	v_mov_b64_e32 v[192:193], s[12:13]
	v_mad_i64_i32 v[190:191], s[0:1], v190, s66, v[192:193]
	v_lshl_add_u64 v[190:191], v[154:155], 1, v[190:191]
	v_pk_fma_f32 v[124:125], v[124:125], v[202:203], v[44:45] op_sel_hi:[1,0,1]
	v_pk_fma_f32 v[126:127], v[126:127], v[202:203], v[46:47] op_sel_hi:[1,0,1]
	v_pk_fma_f32 v[120:121], v[120:121], v[202:203], v[40:41] op_sel_hi:[1,0,1]
	v_pk_fma_f32 v[122:123], v[122:123], v[202:203], v[42:43] op_sel_hi:[1,0,1]
	v_pk_mul_f32 v[192:193], v[124:125], v[216:217] op_sel_hi:[1,0]
	v_pk_mul_f32 v[194:195], v[126:127], v[216:217] op_sel_hi:[1,0]
	v_pk_mul_f32 v[196:197], v[120:121], v[216:217] op_sel_hi:[1,0]
	v_pk_mul_f32 v[198:199], v[122:123], v[216:217] op_sel_hi:[1,0]
	v_exp_f32_e32 v192, v192
	v_exp_f32_e32 v193, v193
	v_exp_f32_e32 v194, v194
	v_exp_f32_e32 v195, v195
	v_exp_f32_e32 v196, v196
	v_exp_f32_e32 v197, v197
	v_exp_f32_e32 v198, v198
	v_exp_f32_e32 v199, v199
	v_pk_add_f32 v[192:193], v[192:193], 1.0 op_sel_hi:[1,0]
	v_pk_add_f32 v[194:195], v[194:195], 1.0 op_sel_hi:[1,0]
	v_pk_add_f32 v[196:197], v[196:197], 1.0 op_sel_hi:[1,0]
	v_pk_add_f32 v[198:199], v[198:199], 1.0 op_sel_hi:[1,0]
	v_rcp_f32_e32 v192, v192
	v_rcp_f32_e32 v193, v193
	v_rcp_f32_e32 v194, v194
	v_rcp_f32_e32 v195, v195
	v_rcp_f32_e32 v196, v196
	v_rcp_f32_e32 v197, v197
	v_rcp_f32_e32 v198, v198
	v_rcp_f32_e32 v199, v199
	v_cvt_pk_bf16_f32 v238, v192, v193
	v_cvt_pk_bf16_f32 v239, v194, v195
	v_cvt_pk_bf16_f32 v240, v196, v197
	v_cvt_pk_bf16_f32 v241, v198, v199
	global_store_dwordx4 v[190:191], v[238:241], off
	v_pk_fma_f32 v[116:117], v[116:117], v[202:203], v[28:29] op_sel_hi:[1,0,1]
	v_pk_fma_f32 v[118:119], v[118:119], v[202:203], v[30:31] op_sel_hi:[1,0,1]
	v_pk_fma_f32 v[112:113], v[112:113], v[202:203], v[24:25] op_sel_hi:[1,0,1]
	v_pk_fma_f32 v[114:115], v[114:115], v[202:203], v[26:27] op_sel_hi:[1,0,1]
	v_pk_mul_f32 v[192:193], v[116:117], v[216:217] op_sel_hi:[1,0]
	v_pk_mul_f32 v[194:195], v[118:119], v[216:217] op_sel_hi:[1,0]
	v_pk_mul_f32 v[196:197], v[112:113], v[216:217] op_sel_hi:[1,0]
	v_pk_mul_f32 v[198:199], v[114:115], v[216:217] op_sel_hi:[1,0]
	v_exp_f32_e32 v192, v192
	v_exp_f32_e32 v193, v193
	v_exp_f32_e32 v194, v194
	v_exp_f32_e32 v195, v195
	v_exp_f32_e32 v196, v196
	v_exp_f32_e32 v197, v197
	v_exp_f32_e32 v198, v198
	v_exp_f32_e32 v199, v199
	v_pk_add_f32 v[192:193], v[192:193], 1.0 op_sel_hi:[1,0]
	v_pk_add_f32 v[194:195], v[194:195], 1.0 op_sel_hi:[1,0]
	v_pk_add_f32 v[196:197], v[196:197], 1.0 op_sel_hi:[1,0]
	v_pk_add_f32 v[198:199], v[198:199], 1.0 op_sel_hi:[1,0]
	v_rcp_f32_e32 v192, v192
	v_rcp_f32_e32 v193, v193
	v_rcp_f32_e32 v194, v194
	v_rcp_f32_e32 v195, v195
	v_rcp_f32_e32 v196, v196
	v_rcp_f32_e32 v197, v197
	v_rcp_f32_e32 v198, v198
	v_rcp_f32_e32 v199, v199
	v_cvt_pk_bf16_f32 v218, v192, v193
	v_cvt_pk_bf16_f32 v219, v194, v195
	v_cvt_pk_bf16_f32 v220, v196, v197
	v_cvt_pk_bf16_f32 v221, v198, v199
	global_store_dwordx4 v[190:191], v[218:221], off offset:256
	v_or_b32_e32 v190, 32, v156
	v_mov_b64_e32 v[192:193], s[12:13]
	v_mad_i64_i32 v[190:191], s[0:1], v190, s66, v[192:193]
	v_lshl_add_u64 v[190:191], v[154:155], 1, v[190:191]
	v_pk_fma_f32 v[108:109], v[108:109], v[204:205], v[44:45] op_sel_hi:[1,0,1]
	v_pk_fma_f32 v[110:111], v[110:111], v[204:205], v[46:47] op_sel_hi:[1,0,1]
	v_pk_fma_f32 v[104:105], v[104:105], v[204:205], v[40:41] op_sel_hi:[1,0,1]
	v_pk_fma_f32 v[106:107], v[106:107], v[204:205], v[42:43] op_sel_hi:[1,0,1]
	v_pk_mul_f32 v[192:193], v[108:109], v[216:217] op_sel_hi:[1,0]
	v_pk_mul_f32 v[194:195], v[110:111], v[216:217] op_sel_hi:[1,0]
	v_pk_mul_f32 v[196:197], v[104:105], v[216:217] op_sel_hi:[1,0]
	v_pk_mul_f32 v[198:199], v[106:107], v[216:217] op_sel_hi:[1,0]
	v_exp_f32_e32 v192, v192
	v_exp_f32_e32 v193, v193
	v_exp_f32_e32 v194, v194
	v_exp_f32_e32 v195, v195
	v_exp_f32_e32 v196, v196
	v_exp_f32_e32 v197, v197
	v_exp_f32_e32 v198, v198
	v_exp_f32_e32 v199, v199
	v_pk_add_f32 v[192:193], v[192:193], 1.0 op_sel_hi:[1,0]
	v_pk_add_f32 v[194:195], v[194:195], 1.0 op_sel_hi:[1,0]
	v_pk_add_f32 v[196:197], v[196:197], 1.0 op_sel_hi:[1,0]
	v_pk_add_f32 v[198:199], v[198:199], 1.0 op_sel_hi:[1,0]
; __device__ __forceinline__ unsigned cvt_pk_bf16(float lo, float hi) { unsigned r; asm volatile("v_cvt_pk_bf16_f32 %0, %1, %2" : "=v"(r) : "v"(lo), "v"(hi)); return r; }
; __device__ __forceinline__ float silu_f(float g) { return g * __builtin_amdgcn_rcpf(1.0f + __expf(-g)); }
; __device__ __forceinline__ float sigm_f(float g) { return __builtin_amdgcn_rcpf(1.0f + __expf(-g)); }
;     __device__ __forceinline__ void operator()(const f32x4 (&acc)[2][2][4][2], const Unit& u, int wr, int wc, int fr, int fq) const {
;     ...
;             for (int m = 0; m < 4; ++m) { const int row = row0 + ai * HALF + m * 16;
;                 const float rs = __builtin_amdgcn_rsqf(ssq[row] * (1.0f / 1024.0f) + 1e-6f);
;                 bf16_t* rowp = O + (size_t)row * 4224 + col0;
; #pragma unroll
;                 for (int bj = 0; bj < 2; ++bj) { f32x4 v0 = acc[ai][bj][m][0] * rs + sv[bj][0], v1 = acc[ai][bj][m][1] * rs + sv[bj][1];
;                     if (mode == 1) {
; #pragma unroll
;                         for (int e = 0; e < 4; ++e) { v0[e] = silu_f(v0[e]); v1[e] = silu_f(v1[e]); }
;                     } else if (mode == 2) {
; #pragma unroll
;                         for (int e = 0; e < 4; ++e) { v0[e] = sigm_f(v0[e]); v1[e] = sigm_f(v1[e]); }
;                     }
;                     u32x4 w; w.x = cvt_pk_bf16(v0[0], v0[1]); w.y = cvt_pk_bf16(v0[2], v0[3]); w.z = cvt_pk_bf16(v1[0], v1[1]); w.w = cvt_pk_bf16(v1[2], v1[3]);
;                     *(u32x4*)(rowp + bj * HALF) = w; } }
	v_rcp_f32_e32 v192, v192
	v_rcp_f32_e32 v193, v193
	v_rcp_f32_e32 v194, v194
	v_rcp_f32_e32 v195, v195
	v_rcp_f32_e32 v196, v196
	v_rcp_f32_e32 v197, v197
	v_rcp_f32_e32 v198, v198
	v_rcp_f32_e32 v199, v199
	v_cvt_pk_bf16_f32 v238, v192, v193
	v_cvt_pk_bf16_f32 v239, v194, v195
	v_cvt_pk_bf16_f32 v240, v196, v197
	v_cvt_pk_bf16_f32 v241, v198, v199
	global_store_dwordx4 v[190:191], v[238:241], off
	v_pk_fma_f32 v[100:101], v[100:101], v[204:205], v[28:29] op_sel_hi:[1,0,1]
	v_pk_fma_f32 v[102:103], v[102:103], v[204:205], v[30:31] op_sel_hi:[1,0,1]
	v_pk_fma_f32 v[96:97], v[96:97], v[204:205], v[24:25] op_sel_hi:[1,0,1]
	v_pk_fma_f32 v[98:99], v[98:99], v[204:205], v[26:27] op_sel_hi:[1,0,1]
	v_pk_mul_f32 v[192:193], v[100:101], v[216:217] op_sel_hi:[1,0]
	v_pk_mul_f32 v[194:195], v[102:103], v[216:217] op_sel_hi:[1,0]
	v_pk_mul_f32 v[196:197], v[96:97], v[216:217] op_sel_hi:[1,0]
	v_pk_mul_f32 v[198:199], v[98:99], v[216:217] op_sel_hi:[1,0]
	v_exp_f32_e32 v192, v192
	v_exp_f32_e32 v193, v193
	v_exp_f32_e32 v194, v194
	v_exp_f32_e32 v195, v195
	v_exp_f32_e32 v196, v196
	v_exp_f32_e32 v197, v197
	v_exp_f32_e32 v198, v198
	v_exp_f32_e32 v199, v199
	v_pk_add_f32 v[192:193], v[192:193], 1.0 op_sel_hi:[1,0]
	v_pk_add_f32 v[194:195], v[194:195], 1.0 op_sel_hi:[1,0]
	v_pk_add_f32 v[196:197], v[196:197], 1.0 op_sel_hi:[1,0]
	v_pk_add_f32 v[198:199], v[198:199], 1.0 op_sel_hi:[1,0]
	v_rcp_f32_e32 v192, v192
	v_rcp_f32_e32 v193, v193
	v_rcp_f32_e32 v194, v194
	v_rcp_f32_e32 v195, v195
	v_rcp_f32_e32 v196, v196
	v_rcp_f32_e32 v197, v197
	v_rcp_f32_e32 v198, v198
	v_rcp_f32_e32 v199, v199
	v_cvt_pk_bf16_f32 v218, v192, v193
	v_cvt_pk_bf16_f32 v219, v194, v195
	v_cvt_pk_bf16_f32 v220, v196, v197
	v_cvt_pk_bf16_f32 v221, v198, v199
	global_store_dwordx4 v[190:191], v[218:221], off offset:256
	v_or_b32_e32 v190, 48, v156
	v_mov_b64_e32 v[192:193], s[12:13]
	v_mad_i64_i32 v[190:191], s[0:1], v190, s66, v[192:193]
	v_lshl_add_u64 v[190:191], v[154:155], 1, v[190:191]
	v_pk_fma_f32 v[92:93], v[92:93], v[206:207], v[44:45] op_sel_hi:[1,0,1]
	v_pk_fma_f32 v[94:95], v[94:95], v[206:207], v[46:47] op_sel_hi:[1,0,1]
	v_pk_fma_f32 v[88:89], v[88:89], v[206:207], v[40:41] op_sel_hi:[1,0,1]
	v_pk_fma_f32 v[90:91], v[90:91], v[206:207], v[42:43] op_sel_hi:[1,0,1]
	v_pk_mul_f32 v[192:193], v[92:93], v[216:217] op_sel_hi:[1,0]
	v_pk_mul_f32 v[194:195], v[94:95], v[216:217] op_sel_hi:[1,0]
	v_pk_mul_f32 v[196:197], v[88:89], v[216:217] op_sel_hi:[1,0]
	v_pk_mul_f32 v[198:199], v[90:91], v[216:217] op_sel_hi:[1,0]
	v_exp_f32_e32 v192, v192
	v_exp_f32_e32 v193, v193
	v_exp_f32_e32 v194, v194
	v_exp_f32_e32 v195, v195
	v_exp_f32_e32 v196, v196
	v_exp_f32_e32 v197, v197
	v_exp_f32_e32 v198, v198
	v_exp_f32_e32 v199, v199
	v_pk_add_f32 v[192:193], v[192:193], 1.0 op_sel_hi:[1,0]
	v_pk_add_f32 v[194:195], v[194:195], 1.0 op_sel_hi:[1,0]
	v_pk_add_f32 v[196:197], v[196:197], 1.0 op_sel_hi:[1,0]
	v_pk_add_f32 v[198:199], v[198:199], 1.0 op_sel_hi:[1,0]
	v_rcp_f32_e32 v192, v192
	v_rcp_f32_e32 v193, v193
	v_rcp_f32_e32 v194, v194
	v_rcp_f32_e32 v195, v195
	v_rcp_f32_e32 v196, v196
	v_rcp_f32_e32 v197, v197
	v_rcp_f32_e32 v198, v198
	v_rcp_f32_e32 v199, v199
	v_cvt_pk_bf16_f32 v238, v192, v193
	v_cvt_pk_bf16_f32 v239, v194, v195
	v_cvt_pk_bf16_f32 v240, v196, v197
	v_cvt_pk_bf16_f32 v241, v198, v199
	global_store_dwordx4 v[190:191], v[238:241], off
	v_pk_fma_f32 v[84:85], v[84:85], v[206:207], v[28:29] op_sel_hi:[1,0,1]
	v_pk_fma_f32 v[86:87], v[86:87], v[206:207], v[30:31] op_sel_hi:[1,0,1]
	v_pk_fma_f32 v[80:81], v[80:81], v[206:207], v[24:25] op_sel_hi:[1,0,1]
	v_pk_fma_f32 v[82:83], v[82:83], v[206:207], v[26:27] op_sel_hi:[1,0,1]
	v_pk_mul_f32 v[192:193], v[84:85], v[216:217] op_sel_hi:[1,0]
	v_pk_mul_f32 v[194:195], v[86:87], v[216:217] op_sel_hi:[1,0]
	v_pk_mul_f32 v[196:197], v[80:81], v[216:217] op_sel_hi:[1,0]
	v_pk_mul_f32 v[198:199], v[82:83], v[216:217] op_sel_hi:[1,0]
	v_exp_f32_e32 v192, v192
	v_exp_f32_e32 v193, v193
	v_exp_f32_e32 v194, v194
	v_exp_f32_e32 v195, v195
	v_exp_f32_e32 v196, v196
	v_exp_f32_e32 v197, v197
	v_exp_f32_e32 v198, v198
	v_exp_f32_e32 v199, v199
	v_pk_add_f32 v[192:193], v[192:193], 1.0 op_sel_hi:[1,0]
	v_pk_add_f32 v[194:195], v[194:195], 1.0 op_sel_hi:[1,0]
	v_pk_add_f32 v[196:197], v[196:197], 1.0 op_sel_hi:[1,0]
	v_pk_add_f32 v[198:199], v[198:199], 1.0 op_sel_hi:[1,0]
	v_rcp_f32_e32 v192, v192
	v_rcp_f32_e32 v193, v193
	v_rcp_f32_e32 v194, v194
	v_rcp_f32_e32 v195, v195
	v_rcp_f32_e32 v196, v196
	v_rcp_f32_e32 v197, v197
	v_rcp_f32_e32 v198, v198
	v_rcp_f32_e32 v199, v199
	v_cvt_pk_bf16_f32 v218, v192, v193
	v_cvt_pk_bf16_f32 v219, v194, v195
	v_cvt_pk_bf16_f32 v220, v196, v197
	v_cvt_pk_bf16_f32 v221, v198, v199
	global_store_dwordx4 v[190:191], v[218:221], off offset:256
	v_add_u32_e32 v190, 0x80, v156
	v_mov_b64_e32 v[192:193], s[12:13]
	v_mad_i64_i32 v[190:191], s[0:1], v190, s66, v[192:193]
	v_lshl_add_u64 v[190:191], v[154:155], 1, v[190:191]
	v_pk_fma_f32 v[76:77], v[76:77], v[208:209], v[44:45] op_sel_hi:[1,0,1]
	v_pk_fma_f32 v[78:79], v[78:79], v[208:209], v[46:47] op_sel_hi:[1,0,1]
	v_pk_fma_f32 v[72:73], v[72:73], v[208:209], v[40:41] op_sel_hi:[1,0,1]
	v_pk_fma_f32 v[74:75], v[74:75], v[208:209], v[42:43] op_sel_hi:[1,0,1]
	v_pk_mul_f32 v[192:193], v[76:77], v[216:217] op_sel_hi:[1,0]
	v_pk_mul_f32 v[194:195], v[78:79], v[216:217] op_sel_hi:[1,0]
	v_pk_mul_f32 v[196:197], v[72:73], v[216:217] op_sel_hi:[1,0]
	v_pk_mul_f32 v[198:199], v[74:75], v[216:217] op_sel_hi:[1,0]
	v_exp_f32_e32 v192, v192
	v_exp_f32_e32 v193, v193
	v_exp_f32_e32 v194, v194
	v_exp_f32_e32 v195, v195
	v_exp_f32_e32 v196, v196
	v_exp_f32_e32 v197, v197
; __device__ __forceinline__ unsigned cvt_pk_bf16(float lo, float hi) { unsigned r; asm volatile("v_cvt_pk_bf16_f32 %0, %1, %2" : "=v"(r) : "v"(lo), "v"(hi)); return r; }
; __device__ __forceinline__ float silu_f(float g) { return g * __builtin_amdgcn_rcpf(1.0f + __expf(-g)); }
; __device__ __forceinline__ float sigm_f(float g) { return __builtin_amdgcn_rcpf(1.0f + __expf(-g)); }
;     __device__ __forceinline__ void operator()(const f32x4 (&acc)[2][2][4][2], const Unit& u, int wr, int wc, int fr, int fq) const {
;     ...
;             for (int m = 0; m < 4; ++m) { const int row = row0 + ai * HALF + m * 16;
;                 const float rs = __builtin_amdgcn_rsqf(ssq[row] * (1.0f / 1024.0f) + 1e-6f);
;                 bf16_t* rowp = O + (size_t)row * 4224 + col0;
; #pragma unroll
;                 for (int bj = 0; bj < 2; ++bj) { f32x4 v0 = acc[ai][bj][m][0] * rs + sv[bj][0], v1 = acc[ai][bj][m][1] * rs + sv[bj][1];
;                     if (mode == 1) {
; #pragma unroll
;                         for (int e = 0; e < 4; ++e) { v0[e] = silu_f(v0[e]); v1[e] = silu_f(v1[e]); }
;                     } else if (mode == 2) {
; #pragma unroll
;                         for (int e = 0; e < 4; ++e) { v0[e] = sigm_f(v0[e]); v1[e] = sigm_f(v1[e]); }
;                     }
;                     u32x4 w; w.x = cvt_pk_bf16(v0[0], v0[1]); w.y = cvt_pk_bf16(v0[2], v0[3]); w.z = cvt_pk_bf16(v1[0], v1[1]); w.w = cvt_pk_bf16(v1[2], v1[3]);
;                     *(u32x4*)(rowp + bj * HALF) = w; } }
	v_exp_f32_e32 v198, v198
	v_exp_f32_e32 v199, v199
	v_pk_add_f32 v[192:193], v[192:193], 1.0 op_sel_hi:[1,0]
	v_pk_add_f32 v[194:195], v[194:195], 1.0 op_sel_hi:[1,0]
	v_pk_add_f32 v[196:197], v[196:197], 1.0 op_sel_hi:[1,0]
	v_pk_add_f32 v[198:199], v[198:199], 1.0 op_sel_hi:[1,0]
	v_rcp_f32_e32 v192, v192
	v_rcp_f32_e32 v193, v193
	v_rcp_f32_e32 v194, v194
	v_rcp_f32_e32 v195, v195
	v_rcp_f32_e32 v196, v196
	v_rcp_f32_e32 v197, v197
	v_rcp_f32_e32 v198, v198
	v_rcp_f32_e32 v199, v199
	v_cvt_pk_bf16_f32 v238, v192, v193
	v_cvt_pk_bf16_f32 v239, v194, v195
	v_cvt_pk_bf16_f32 v240, v196, v197
	v_cvt_pk_bf16_f32 v241, v198, v199
	global_store_dwordx4 v[190:191], v[238:241], off
	v_pk_fma_f32 v[68:69], v[68:69], v[208:209], v[28:29] op_sel_hi:[1,0,1]
	v_pk_fma_f32 v[70:71], v[70:71], v[208:209], v[30:31] op_sel_hi:[1,0,1]
	v_pk_fma_f32 v[64:65], v[64:65], v[208:209], v[24:25] op_sel_hi:[1,0,1]
	v_pk_fma_f32 v[66:67], v[66:67], v[208:209], v[26:27] op_sel_hi:[1,0,1]
	v_pk_mul_f32 v[192:193], v[68:69], v[216:217] op_sel_hi:[1,0]
	v_pk_mul_f32 v[194:195], v[70:71], v[216:217] op_sel_hi:[1,0]
	v_pk_mul_f32 v[196:197], v[64:65], v[216:217] op_sel_hi:[1,0]
	v_pk_mul_f32 v[198:199], v[66:67], v[216:217] op_sel_hi:[1,0]
	v_exp_f32_e32 v192, v192
	v_exp_f32_e32 v193, v193
	v_exp_f32_e32 v194, v194
	v_exp_f32_e32 v195, v195
	v_exp_f32_e32 v196, v196
	v_exp_f32_e32 v197, v197
	v_exp_f32_e32 v198, v198
	v_exp_f32_e32 v199, v199
	v_pk_add_f32 v[192:193], v[192:193], 1.0 op_sel_hi:[1,0]
	v_pk_add_f32 v[194:195], v[194:195], 1.0 op_sel_hi:[1,0]
	v_pk_add_f32 v[196:197], v[196:197], 1.0 op_sel_hi:[1,0]
	v_pk_add_f32 v[198:199], v[198:199], 1.0 op_sel_hi:[1,0]
	v_rcp_f32_e32 v192, v192
	v_rcp_f32_e32 v193, v193
	v_rcp_f32_e32 v194, v194
	v_rcp_f32_e32 v195, v195
	v_rcp_f32_e32 v196, v196
	v_rcp_f32_e32 v197, v197
	v_rcp_f32_e32 v198, v198
	v_rcp_f32_e32 v199, v199
	v_cvt_pk_bf16_f32 v218, v192, v193
	v_cvt_pk_bf16_f32 v219, v194, v195
	v_cvt_pk_bf16_f32 v220, v196, v197
	v_cvt_pk_bf16_f32 v221, v198, v199
	global_store_dwordx4 v[190:191], v[218:221], off offset:256
	v_add_u32_e32 v190, 0x90, v156
	v_mov_b64_e32 v[192:193], s[12:13]
	v_mad_i64_i32 v[190:191], s[0:1], v190, s66, v[192:193]
	v_lshl_add_u64 v[190:191], v[154:155], 1, v[190:191]
	v_pk_fma_f32 v[60:61], v[60:61], v[210:211], v[44:45] op_sel_hi:[1,0,1]
	v_pk_fma_f32 v[62:63], v[62:63], v[210:211], v[46:47] op_sel_hi:[1,0,1]
	v_pk_fma_f32 v[56:57], v[56:57], v[210:211], v[40:41] op_sel_hi:[1,0,1]
	v_pk_fma_f32 v[58:59], v[58:59], v[210:211], v[42:43] op_sel_hi:[1,0,1]
	v_pk_mul_f32 v[192:193], v[60:61], v[216:217] op_sel_hi:[1,0]
	v_pk_mul_f32 v[194:195], v[62:63], v[216:217] op_sel_hi:[1,0]
	v_pk_mul_f32 v[196:197], v[56:57], v[216:217] op_sel_hi:[1,0]
	v_pk_mul_f32 v[198:199], v[58:59], v[216:217] op_sel_hi:[1,0]
	v_exp_f32_e32 v192, v192
	v_exp_f32_e32 v193, v193
	v_exp_f32_e32 v194, v194
	v_exp_f32_e32 v195, v195
	v_exp_f32_e32 v196, v196
	v_exp_f32_e32 v197, v197
	v_exp_f32_e32 v198, v198
	v_exp_f32_e32 v199, v199
	v_pk_add_f32 v[192:193], v[192:193], 1.0 op_sel_hi:[1,0]
	v_pk_add_f32 v[194:195], v[194:195], 1.0 op_sel_hi:[1,0]
	v_pk_add_f32 v[196:197], v[196:197], 1.0 op_sel_hi:[1,0]
	v_pk_add_f32 v[198:199], v[198:199], 1.0 op_sel_hi:[1,0]
	v_rcp_f32_e32 v192, v192
	v_rcp_f32_e32 v193, v193
	v_rcp_f32_e32 v194, v194
	v_rcp_f32_e32 v195, v195
	v_rcp_f32_e32 v196, v196
	v_rcp_f32_e32 v197, v197
	v_rcp_f32_e32 v198, v198
	v_rcp_f32_e32 v199, v199
	v_cvt_pk_bf16_f32 v238, v192, v193
	v_cvt_pk_bf16_f32 v239, v194, v195
	v_cvt_pk_bf16_f32 v240, v196, v197
	v_cvt_pk_bf16_f32 v241, v198, v199
	global_store_dwordx4 v[190:191], v[238:241], off
	v_pk_fma_f32 v[52:53], v[52:53], v[210:211], v[28:29] op_sel_hi:[1,0,1]
	v_pk_fma_f32 v[54:55], v[54:55], v[210:211], v[30:31] op_sel_hi:[1,0,1]
	v_pk_fma_f32 v[48:49], v[48:49], v[210:211], v[24:25] op_sel_hi:[1,0,1]
	v_pk_fma_f32 v[50:51], v[50:51], v[210:211], v[26:27] op_sel_hi:[1,0,1]
	v_pk_mul_f32 v[192:193], v[52:53], v[216:217] op_sel_hi:[1,0]
	v_pk_mul_f32 v[194:195], v[54:55], v[216:217] op_sel_hi:[1,0]
	v_pk_mul_f32 v[196:197], v[48:49], v[216:217] op_sel_hi:[1,0]
	v_pk_mul_f32 v[198:199], v[50:51], v[216:217] op_sel_hi:[1,0]
	v_exp_f32_e32 v192, v192
	v_exp_f32_e32 v193, v193
	v_exp_f32_e32 v194, v194
	v_exp_f32_e32 v195, v195
	v_exp_f32_e32 v196, v196
	v_exp_f32_e32 v197, v197
	v_exp_f32_e32 v198, v198
	v_exp_f32_e32 v199, v199
	v_pk_add_f32 v[192:193], v[192:193], 1.0 op_sel_hi:[1,0]
	v_pk_add_f32 v[194:195], v[194:195], 1.0 op_sel_hi:[1,0]
	v_pk_add_f32 v[196:197], v[196:197], 1.0 op_sel_hi:[1,0]
	v_pk_add_f32 v[198:199], v[198:199], 1.0 op_sel_hi:[1,0]
	v_rcp_f32_e32 v192, v192
	v_rcp_f32_e32 v193, v193
	v_rcp_f32_e32 v194, v194
	v_rcp_f32_e32 v195, v195
	v_rcp_f32_e32 v196, v196
	v_rcp_f32_e32 v197, v197
	v_rcp_f32_e32 v198, v198
	v_rcp_f32_e32 v199, v199
	v_cvt_pk_bf16_f32 v218, v192, v193
	v_cvt_pk_bf16_f32 v219, v194, v195
	v_cvt_pk_bf16_f32 v220, v196, v197
	v_cvt_pk_bf16_f32 v221, v198, v199
	global_store_dwordx4 v[190:191], v[218:221], off offset:256
	v_add_u32_e32 v190, 0xa0, v156
	v_mov_b64_e32 v[192:193], s[12:13]
	v_mad_i64_i32 v[190:191], s[0:1], v190, s66, v[192:193]
	v_lshl_add_u64 v[190:191], v[154:155], 1, v[190:191]
	v_pk_fma_f32 v[36:37], v[36:37], v[212:213], v[44:45] op_sel_hi:[1,0,1]
	v_pk_fma_f32 v[38:39], v[38:39], v[212:213], v[46:47] op_sel_hi:[1,0,1]
	v_pk_fma_f32 v[32:33], v[32:33], v[212:213], v[40:41] op_sel_hi:[1,0,1]
	v_pk_fma_f32 v[34:35], v[34:35], v[212:213], v[42:43] op_sel_hi:[1,0,1]
	v_pk_mul_f32 v[192:193], v[36:37], v[216:217] op_sel_hi:[1,0]
; __device__ __forceinline__ unsigned cvt_pk_bf16(float lo, float hi) { unsigned r; asm volatile("v_cvt_pk_bf16_f32 %0, %1, %2" : "=v"(r) : "v"(lo), "v"(hi)); return r; }
; #define PG8_BAR __builtin_amdgcn_s_barrier()
; __device__ __forceinline__ float silu_f(float g) { return g * __builtin_amdgcn_rcpf(1.0f + __expf(-g)); }
; __device__ __forceinline__ float sigm_f(float g) { return __builtin_amdgcn_rcpf(1.0f + __expf(-g)); }
; template <class Epi, class Sched, bool ALIGN_EPI = false, bool SP2 = false>
; __device__ __forceinline__ void gemm_phase(PG8_LAS unsigned char* lds, const Gemm g, const Sched& S, const Epi& E, const int tid_in) {
;     ...
;         if constexpr (ALIGN_EPI) { if (wr == 0) PG8_BAR; }
;         if constexpr (!Epi::AFTER_DRAIN) { E(acc, cur, wr, wc, fr, fq); S.done(cur); }
;         if (!has_next) break;
; #pragma unroll
;         for (int a = 0; a < 2; ++a)
; #pragma unroll
;             for (int b = 0; b < 2; ++b)
; #pragma unroll
;                 for (int m = 0; m < 4; ++m)
; #pragma unroll
;                     for (int n = 0; n < 2; ++n) acc[a][b][m][n] = (f32x4){0.f, 0.f, 0.f, 0.f};
;         cur = nxt; cA = nA; cB = nB; ++ui;
;         if constexpr (ALIGN_EPI) { if (wr == 1) PG8_BAR; }
;     __device__ __forceinline__ void operator()(const f32x4 (&acc)[2][2][4][2], const Unit& u, int wr, int wc, int fr, int fq) const {
;     ...
;             for (int m = 0; m < 4; ++m) { const int row = row0 + ai * HALF + m * 16;
;                 const float rs = __builtin_amdgcn_rsqf(ssq[row] * (1.0f / 1024.0f) + 1e-6f);
;                 bf16_t* rowp = O + (size_t)row * 4224 + col0;
; #pragma unroll
;                 for (int bj = 0; bj < 2; ++bj) { f32x4 v0 = acc[ai][bj][m][0] * rs + sv[bj][0], v1 = acc[ai][bj][m][1] * rs + sv[bj][1];
;                     if (mode == 1) {
; #pragma unroll
;                         for (int e = 0; e < 4; ++e) { v0[e] = silu_f(v0[e]); v1[e] = silu_f(v1[e]); }
;                     } else if (mode == 2) {
; #pragma unroll
;                         for (int e = 0; e < 4; ++e) { v0[e] = sigm_f(v0[e]); v1[e] = sigm_f(v1[e]); }
;                     }
;                     u32x4 w; w.x = cvt_pk_bf16(v0[0], v0[1]); w.y = cvt_pk_bf16(v0[2], v0[3]); w.z = cvt_pk_bf16(v1[0], v1[1]); w.w = cvt_pk_bf16(v1[2], v1[3]);
;                     *(u32x4*)(rowp + bj * HALF) = w; } }
	v_pk_mul_f32 v[194:195], v[38:39], v[216:217] op_sel_hi:[1,0]
	v_pk_mul_f32 v[196:197], v[32:33], v[216:217] op_sel_hi:[1,0]
	v_pk_mul_f32 v[198:199], v[34:35], v[216:217] op_sel_hi:[1,0]
	v_exp_f32_e32 v192, v192
	v_exp_f32_e32 v193, v193
	v_exp_f32_e32 v194, v194
	v_exp_f32_e32 v195, v195
	v_exp_f32_e32 v196, v196
	v_exp_f32_e32 v197, v197
	v_exp_f32_e32 v198, v198
	v_exp_f32_e32 v199, v199
	v_pk_add_f32 v[192:193], v[192:193], 1.0 op_sel_hi:[1,0]
	v_pk_add_f32 v[194:195], v[194:195], 1.0 op_sel_hi:[1,0]
	v_pk_add_f32 v[196:197], v[196:197], 1.0 op_sel_hi:[1,0]
	v_pk_add_f32 v[198:199], v[198:199], 1.0 op_sel_hi:[1,0]
	v_rcp_f32_e32 v192, v192
	v_rcp_f32_e32 v193, v193
	v_rcp_f32_e32 v194, v194
	v_rcp_f32_e32 v195, v195
	v_rcp_f32_e32 v196, v196
	v_rcp_f32_e32 v197, v197
	v_rcp_f32_e32 v198, v198
	v_rcp_f32_e32 v199, v199
	v_cvt_pk_bf16_f32 v238, v192, v193
	v_cvt_pk_bf16_f32 v239, v194, v195
	v_cvt_pk_bf16_f32 v240, v196, v197
	v_cvt_pk_bf16_f32 v241, v198, v199
	global_store_dwordx4 v[190:191], v[238:241], off
	v_pk_fma_f32 v[20:21], v[20:21], v[212:213], v[28:29] op_sel_hi:[1,0,1]
	v_pk_fma_f32 v[22:23], v[22:23], v[212:213], v[30:31] op_sel_hi:[1,0,1]
	v_pk_fma_f32 v[16:17], v[16:17], v[212:213], v[24:25] op_sel_hi:[1,0,1]
	v_pk_fma_f32 v[18:19], v[18:19], v[212:213], v[26:27] op_sel_hi:[1,0,1]
	v_pk_mul_f32 v[192:193], v[20:21], v[216:217] op_sel_hi:[1,0]
	v_pk_mul_f32 v[194:195], v[22:23], v[216:217] op_sel_hi:[1,0]
	v_pk_mul_f32 v[196:197], v[16:17], v[216:217] op_sel_hi:[1,0]
	v_pk_mul_f32 v[198:199], v[18:19], v[216:217] op_sel_hi:[1,0]
	v_exp_f32_e32 v192, v192
	v_exp_f32_e32 v193, v193
	v_exp_f32_e32 v194, v194
	v_exp_f32_e32 v195, v195
	v_exp_f32_e32 v196, v196
	v_exp_f32_e32 v197, v197
	v_exp_f32_e32 v198, v198
	v_exp_f32_e32 v199, v199
	v_pk_add_f32 v[192:193], v[192:193], 1.0 op_sel_hi:[1,0]
	v_pk_add_f32 v[194:195], v[194:195], 1.0 op_sel_hi:[1,0]
	v_pk_add_f32 v[196:197], v[196:197], 1.0 op_sel_hi:[1,0]
	v_pk_add_f32 v[198:199], v[198:199], 1.0 op_sel_hi:[1,0]
	v_rcp_f32_e32 v192, v192
	v_rcp_f32_e32 v193, v193
	v_rcp_f32_e32 v194, v194
	v_rcp_f32_e32 v195, v195
	v_rcp_f32_e32 v196, v196
	v_rcp_f32_e32 v197, v197
	v_rcp_f32_e32 v198, v198
	v_rcp_f32_e32 v199, v199
	v_cvt_pk_bf16_f32 v218, v192, v193
	v_cvt_pk_bf16_f32 v219, v194, v195
	v_cvt_pk_bf16_f32 v220, v196, v197
	v_cvt_pk_bf16_f32 v221, v198, v199
	global_store_dwordx4 v[190:191], v[218:221], off offset:256
	v_add_u32_e32 v190, 0xb0, v156
	v_mov_b64_e32 v[192:193], s[12:13]
	v_mad_i64_i32 v[190:191], s[0:1], v190, s66, v[192:193]
	v_lshl_add_u64 v[190:191], v[154:155], 1, v[190:191]
	v_pk_fma_f32 v[12:13], v[12:13], v[214:215], v[44:45] op_sel_hi:[1,0,1]
	v_pk_fma_f32 v[14:15], v[14:15], v[214:215], v[46:47] op_sel_hi:[1,0,1]
	v_pk_fma_f32 v[8:9], v[8:9], v[214:215], v[40:41] op_sel_hi:[1,0,1]
	v_pk_fma_f32 v[10:11], v[10:11], v[214:215], v[42:43] op_sel_hi:[1,0,1]
	v_pk_mul_f32 v[192:193], v[12:13], v[216:217] op_sel_hi:[1,0]
	v_pk_mul_f32 v[194:195], v[14:15], v[216:217] op_sel_hi:[1,0]
	v_pk_mul_f32 v[196:197], v[8:9], v[216:217] op_sel_hi:[1,0]
	v_pk_mul_f32 v[198:199], v[10:11], v[216:217] op_sel_hi:[1,0]
	v_exp_f32_e32 v192, v192
	v_exp_f32_e32 v193, v193
	v_exp_f32_e32 v194, v194
	v_exp_f32_e32 v195, v195
	v_exp_f32_e32 v196, v196
	v_exp_f32_e32 v197, v197
	v_exp_f32_e32 v198, v198
	v_exp_f32_e32 v199, v199
	v_pk_add_f32 v[192:193], v[192:193], 1.0 op_sel_hi:[1,0]
	v_pk_add_f32 v[194:195], v[194:195], 1.0 op_sel_hi:[1,0]
	v_pk_add_f32 v[196:197], v[196:197], 1.0 op_sel_hi:[1,0]
	v_pk_add_f32 v[198:199], v[198:199], 1.0 op_sel_hi:[1,0]
	v_rcp_f32_e32 v192, v192
	v_rcp_f32_e32 v193, v193
	v_rcp_f32_e32 v194, v194
	v_rcp_f32_e32 v195, v195
	v_rcp_f32_e32 v196, v196
	v_rcp_f32_e32 v197, v197
	v_rcp_f32_e32 v198, v198
	v_rcp_f32_e32 v199, v199
	v_cvt_pk_bf16_f32 v238, v192, v193
	v_cvt_pk_bf16_f32 v239, v194, v195
	v_cvt_pk_bf16_f32 v240, v196, v197
	v_cvt_pk_bf16_f32 v241, v198, v199
	global_store_dwordx4 v[190:191], v[238:241], off
	v_pk_fma_f32 v[4:5], v[4:5], v[214:215], v[28:29] op_sel_hi:[1,0,1]
	v_pk_fma_f32 v[6:7], v[6:7], v[214:215], v[30:31] op_sel_hi:[1,0,1]
	v_pk_fma_f32 v[0:1], v[0:1], v[214:215], v[24:25] op_sel_hi:[1,0,1]
	v_pk_fma_f32 v[2:3], v[2:3], v[214:215], v[26:27] op_sel_hi:[1,0,1]
	v_pk_mul_f32 v[192:193], v[4:5], v[216:217] op_sel_hi:[1,0]
	v_pk_mul_f32 v[194:195], v[6:7], v[216:217] op_sel_hi:[1,0]
	v_pk_mul_f32 v[196:197], v[0:1], v[216:217] op_sel_hi:[1,0]
	v_pk_mul_f32 v[198:199], v[2:3], v[216:217] op_sel_hi:[1,0]
	v_exp_f32_e32 v192, v192
	v_exp_f32_e32 v193, v193
	v_exp_f32_e32 v194, v194
	v_exp_f32_e32 v195, v195
	v_exp_f32_e32 v196, v196
	v_exp_f32_e32 v197, v197
	v_exp_f32_e32 v198, v198
	v_exp_f32_e32 v199, v199
	v_pk_add_f32 v[192:193], v[192:193], 1.0 op_sel_hi:[1,0]
	v_pk_add_f32 v[194:195], v[194:195], 1.0 op_sel_hi:[1,0]
	v_pk_add_f32 v[196:197], v[196:197], 1.0 op_sel_hi:[1,0]
	v_pk_add_f32 v[198:199], v[198:199], 1.0 op_sel_hi:[1,0]
	v_rcp_f32_e32 v192, v192
	v_rcp_f32_e32 v193, v193
	v_rcp_f32_e32 v194, v194
	v_rcp_f32_e32 v195, v195
	v_rcp_f32_e32 v196, v196
	v_rcp_f32_e32 v197, v197
	v_rcp_f32_e32 v198, v198
	v_rcp_f32_e32 v199, v199
	v_cvt_pk_bf16_f32 v218, v192, v193
	v_cvt_pk_bf16_f32 v219, v194, v195
	v_cvt_pk_bf16_f32 v220, v196, v197
	v_cvt_pk_bf16_f32 v221, v198, v199
	global_store_dwordx4 v[190:191], v[218:221], off offset:256
.Lpj_done:
	s_andn2_b64 vcc, exec, s[42:43]
	s_mov_b64 s[40:41], -1
	s_mov_b32 s20, 0xffff
	s_cbranch_vccnz .LBB0_189
	s_andn2_b64 vcc, exec, s[30:31]
	s_cbranch_vccnz .LBB0_188
	s_barrier
	s_branch .LBB0_188
